# S5 recurrence step contracted to four fused multiply-adds (227 of 248 steps)
# speedup vs baseline: 1.0082x; 1.0082x over previous
.LBB0_275:
	s_or_b64 exec, exec, s[4:5]
	s_waitcnt lgkmcnt(0)
	v_mfma_f32_16x16x32_bf16 v[42:45], v[72:75], v[42:45], 0
	v_mul_f32_e32 v63, v33, v62
	v_fma_f32 v63, v32, v0, -v63
	v_mul_f32_e32 v0, v33, v0
	v_mfma_f32_16x16x32_bf16 v[68:71], v[72:75], v[68:71], 0
	s_nop 7
	ds_write2_b32 v80, v42, v68 offset1:16
	ds_write2_b32 v80, v43, v69 offset0:132 offset1:148
	ds_write2_b32 v82, v44, v70 offset0:8 offset1:24
	v_mfma_f32_16x16x32_bf16 v[64:67], v[72:75], v[64:67], 0
	v_fmac_f32_e32 v0, v32, v62
	v_readlane_b32 s4, v245, 53
	v_mfma_f32_16x16x32_bf16 v[50:53], v[72:75], v[50:53], 0
	ds_write2_b32 v82, v45, v71 offset0:140 offset1:156
	s_nop 6
	ds_write2_b32 v80, v64, v50 offset0:32 offset1:48
	ds_write2_b32 v80, v65, v51 offset0:164 offset1:180
	v_mfma_f32_16x16x32_bf16 v[54:57], v[72:75], v[54:57], 0
	v_mfma_f32_16x16x32_bf16 v[42:45], v[72:75], v[46:49], 0
	ds_write2_b32 v82, v66, v52 offset0:40 offset1:56
	ds_write2_b32 v82, v67, v53 offset0:172 offset1:188
	s_nop 5
	ds_write2_b32 v80, v54, v42 offset0:64 offset1:80
	ds_write2_b32 v80, v55, v43 offset0:196 offset1:212
	ds_write2_b32 v82, v56, v44 offset0:72 offset1:88
	ds_write2_b32 v82, v57, v45 offset0:204 offset1:220
	v_mfma_f32_16x16x32_bf16 v[38:41], v[72:75], v[38:41], 0
	v_mfma_f32_16x16x32_bf16 v[34:37], v[72:75], v[34:37], 0
	s_nop 7
	ds_write2_b32 v80, v38, v34 offset0:96 offset1:112
	ds_write2_b32 v80, v39, v35 offset0:228 offset1:244
	ds_write2_b32 v82, v40, v36 offset0:104 offset1:120
	ds_write2_b32 v82, v41, v37 offset0:236 offset1:252
	s_waitcnt lgkmcnt(0)
	ds_read2st64_b32 v[10:11], v84 offset0:42 offset1:43
	ds_read2st64_b32 v[34:35], v85 offset0:40 offset1:41
	ds_read2st64_b32 v[36:37], v86 offset0:38 offset1:39
	ds_read2st64_b32 v[38:39], v87 offset0:36 offset1:37
	ds_read2st64_b32 v[40:41], v88 offset0:34 offset1:35
	ds_read2st64_b32 v[42:43], v89 offset0:32 offset1:33
	ds_read2st64_b32 v[44:45], v90 offset0:30 offset1:31
	ds_read2st64_b32 v[46:47], v91 offset0:28 offset1:29
	ds_read2st64_b32 v[48:49], v92 offset0:26 offset1:27
	ds_read2st64_b32 v[50:51], v93 offset0:24 offset1:25
	ds_read2st64_b32 v[52:53], v94 offset0:22 offset1:23
	ds_read2st64_b32 v[54:55], v95 offset0:20 offset1:21
	ds_read2st64_b32 v[56:57], v96 offset0:18 offset1:19
	ds_read2st64_b32 v[64:65], v97 offset0:16 offset1:17
	ds_read2st64_b32 v[66:67], v98 offset0:14 offset1:15
	ds_read2st64_b32 v[68:69], v83 offset0:12 offset1:13
	s_waitcnt lgkmcnt(14)
	v_add_f32_e32 v10, v63, v10
	v_add_f32_e32 v0, v0, v11
	v_cvt_pk_bf16_f32 v11, v10, v0
	v_fma_f32 v62, v33, v10, v35
	v_fma_f32 v34, v32, v10, v34
	v_fma_f32 v34, -v33, v0, v34
	v_fma_f32 v0, v32, v0, v62
	v_cvt_pk_bf16_f32 v10, v34, v0
	ds_write2_b32 v99, v10, v11 offset0:120 offset1:188
	s_waitcnt lgkmcnt(14)
	v_fma_f32 v11, v33, v34, v37
	v_fma_f32 v10, v32, v34, v36
	v_fma_f32 v10, -v33, v0, v10
	v_fma_f32 v0, v32, v0, v11
	v_cvt_pk_bf16_f32 v11, v10, v0
	s_waitcnt lgkmcnt(13)
	v_fma_f32 v34, -v0, v33, v38
	v_fma_f32 v0, v0, v32, v39
	v_fma_f32 v0, v10, v33, v0
	v_fma_f32 v34, v10, v32, v34
	v_cvt_pk_bf16_f32 v10, v34, v0
	ds_write2_b32 v100, v10, v11 offset0:112 offset1:180
	s_waitcnt lgkmcnt(13)
	v_fma_f32 v11, v33, v34, v41
	v_fma_f32 v10, v32, v34, v40
	v_fma_f32 v10, -v33, v0, v10
	v_fma_f32 v0, v32, v0, v11
	v_cvt_pk_bf16_f32 v11, v10, v0
	s_waitcnt lgkmcnt(12)
	v_fma_f32 v34, -v0, v33, v42
	v_fma_f32 v0, v0, v32, v43
	v_fma_f32 v0, v10, v33, v0
	v_fma_f32 v34, v10, v32, v34
	v_cvt_pk_bf16_f32 v10, v34, v0
	ds_write2_b32 v101, v10, v11 offset0:104 offset1:172
	s_waitcnt lgkmcnt(12)
	v_fma_f32 v11, v33, v34, v45
	v_fma_f32 v10, v32, v34, v44
	v_fma_f32 v10, -v33, v0, v10
	v_fma_f32 v0, v32, v0, v11
	v_cvt_pk_bf16_f32 v11, v10, v0
	s_waitcnt lgkmcnt(11)
	v_fma_f32 v34, -v0, v33, v46
	v_fma_f32 v0, v0, v32, v47
	v_fma_f32 v0, v10, v33, v0
	v_fma_f32 v34, v10, v32, v34
	v_cvt_pk_bf16_f32 v10, v34, v0
	ds_write2_b32 v102, v10, v11 offset0:96 offset1:164
	s_waitcnt lgkmcnt(11)
	v_fma_f32 v11, v33, v34, v49
	v_fma_f32 v10, v32, v34, v48
	v_fma_f32 v10, -v33, v0, v10
	v_fma_f32 v0, v32, v0, v11
	v_cvt_pk_bf16_f32 v11, v10, v0
	s_waitcnt lgkmcnt(10)
	v_fma_f32 v34, -v0, v33, v50
	v_fma_f32 v0, v0, v32, v51
	v_fma_f32 v0, v10, v33, v0
	v_fma_f32 v34, v10, v32, v34
	v_cvt_pk_bf16_f32 v10, v34, v0
	ds_write2_b32 v103, v10, v11 offset0:88 offset1:156
	s_waitcnt lgkmcnt(10)
	v_fma_f32 v11, v33, v34, v53
	v_fma_f32 v10, v32, v34, v52
	v_fma_f32 v10, -v33, v0, v10
	v_fma_f32 v0, v32, v0, v11
	v_cvt_pk_bf16_f32 v11, v10, v0
	s_waitcnt lgkmcnt(9)
	v_fma_f32 v34, -v0, v33, v54
	v_fma_f32 v0, v0, v32, v55
	v_fma_f32 v0, v10, v33, v0
	v_fma_f32 v34, v10, v32, v34
	v_cvt_pk_bf16_f32 v10, v34, v0
	ds_write2_b32 v104, v10, v11 offset0:80 offset1:148
	s_waitcnt lgkmcnt(9)
	v_fma_f32 v11, v33, v34, v57
	v_fma_f32 v10, v32, v34, v56
	v_fma_f32 v10, -v33, v0, v10
	v_fma_f32 v0, v32, v0, v11
	v_cvt_pk_bf16_f32 v11, v10, v0
	s_waitcnt lgkmcnt(8)
	v_fma_f32 v34, -v0, v33, v64
	v_fma_f32 v0, v0, v32, v65
	v_fma_f32 v0, v10, v33, v0
	v_fma_f32 v34, v10, v32, v34
	v_cvt_pk_bf16_f32 v10, v34, v0
	ds_write2_b32 v105, v10, v11 offset0:72 offset1:140
	s_waitcnt lgkmcnt(8)
	v_fma_f32 v11, v33, v34, v67
	v_fma_f32 v10, v32, v34, v66
	v_fma_f32 v10, -v33, v0, v10
	v_fma_f32 v0, v32, v0, v11
	v_cvt_pk_bf16_f32 v11, v10, v0
	s_waitcnt lgkmcnt(7)
	v_fma_f32 v34, -v0, v33, v68
	v_fma_f32 v0, v0, v32, v69
	v_fma_f32 v0, v10, v33, v0
	v_fma_f32 v34, v10, v32, v34
	v_cvt_pk_bf16_f32 v0, v34, v0
	ds_write2_b32 v106, v0, v11 offset0:64 offset1:132
	s_waitcnt lgkmcnt(0)
	v_mov_b32_e32 v0, s4
	ds_read_b64 v[10:11], v0
	s_lshr_b32 s4, s23, 6
	v_lshrrev_b32_e32 v0, 2, v78
	v_and_b32_e32 v46, 15, v78
	s_mulk_i32 s4, 0x3e00
	v_and_b32_e32 v47, 12, v0
	ds_read_b128 v[32:35], v79 offset:11520
	ds_read_b128 v[36:39], v79 offset:11584
	s_add_i32 s4, s4, 0
	v_lshlrev_b32_e32 v0, 1, v46
	v_mul_u32_u24_e32 v41, 48, v47
	v_add3_u32 v48, s4, v0, v41
	s_waitcnt lgkmcnt(2)
	v_readfirstlane_b32 s4, v11
	v_readfirstlane_b32 s5, v10
	s_waitcnt lgkmcnt(1)
	v_mfma_f32_16x16x32_bf16 v[2:5], v[32:35], v[20:23], v[2:5]
	v_mov_b32_e32 v11, s4
	v_mov_b32_e32 v10, s5
	v_readlane_b32 s4, v245, 4
	s_add_i32 s4, s0, s4
	v_mov_b32_e32 v40, s59
	v_or_b32_e32 v20, s4, v46
	v_ashrrev_i32_e32 v21, 31, v20
	v_lshl_add_u64 v[10:11], v[20:21], 2, v[10:11]
	ds_read_u16 v49, v48
	ds_read_b64 v[44:45], v40
	global_load_dword v10, v[10:11], off
	ds_read_b128 v[40:43], v79 offset:11648
	ds_read_b128 v[20:23], v79 offset:11712
	s_waitcnt lgkmcnt(0)
	v_mfma_f32_16x16x32_bf16 v[2:5], v[36:39], v[28:31], v[2:5]
	v_readlane_b32 s5, v245, 5
	v_readfirstlane_b32 s5, v44
	s_lshl_b64 s[0:1], s[0:1], 1
	v_mfma_f32_16x16x32_bf16 v[2:5], v[40:43], v[24:27], v[2:5]
	v_readfirstlane_b32 s4, v45
	s_add_u32 s0, s5, s0
	s_addc_u32 s1, s4, s1
	v_mfma_f32_16x16x32_bf16 v[16:19], v[20:23], v[16:19], v[2:5]
	s_lshl_b32 s4, s22, 6
	s_add_i32 s10, s10, s54
	s_add_i32 s17, s17, s60
	s_nop 0
	v_lshl_add_u64 v[2:3], s[0:1], 0, v[0:1]
	v_lshlrev_b32_e32 v0, 16, v49
	s_mov_b64 s[0:1], 0xcc00000
	v_lshl_add_u64 v[2:3], v[2:3], 0, s[0:1]
	s_lshl_b32 s0, s20, 12
	s_lshl_b32 s1, s20, 8
	s_add_i32 s0, s22, s0
	s_add_i32 s1, s1, s4
	s_add_i32 s0, s0, -4
	s_add_i32 s1, s1, 0x8000
	v_lshl_add_u32 v5, v47, 6, s0
	s_waitcnt vmcnt(0)
	v_fma_f32 v0, v10, v0, v16
	v_mul_f32_e32 v4, v0, v0
	v_fmamk_f32 v4, v4, 0xbdd2d3e8, v211
	v_mul_f32_e32 v4, v0, v4
	v_exp_f32_e32 v4, v4
	s_nop 0
	v_add_f32_e32 v4, 1.0, v4
	v_rcp_f32_e32 v4, v4
	s_nop 0
	v_mul_f32_e32 v0, v0, v4
	v_or_b32_e32 v4, s1, v47
	v_cndmask_b32_e64 v4, v5, v4, s[36:37]
	v_ashrrev_i32_e32 v5, 31, v4
	v_lshlrev_b64 v[4:5], 9, v[4:5]
	v_cvt_pk_bf16_f32 v0, v0, s0
	v_lshl_add_u64 v[4:5], v[2:3], 0, v[4:5]
	global_store_short v[4:5], v0, off
	ds_read_u16 v0, v48 offset:48
	v_or_b32_e32 v5, 1, v47
	s_waitcnt lgkmcnt(0)
	v_lshlrev_b32_e32 v0, 16, v0
	v_fma_f32 v0, v10, v0, v17
	v_mul_f32_e32 v4, v0, v0
	v_fmamk_f32 v4, v4, 0xbdd2d3e8, v211
	v_mul_f32_e32 v4, v0, v4
	v_exp_f32_e32 v4, v4
	s_nop 0
	v_add_f32_e32 v4, 1.0, v4
	v_rcp_f32_e32 v4, v4
	s_nop 0
	v_mul_f32_e32 v0, v0, v4
	v_or_b32_e32 v4, s1, v5
	v_lshl_add_u32 v5, v5, 6, s0
	v_cndmask_b32_e64 v4, v5, v4, s[36:37]
	v_ashrrev_i32_e32 v5, 31, v4
	v_lshlrev_b64 v[4:5], 9, v[4:5]
	v_cvt_pk_bf16_f32 v0, v0, s0
	v_lshl_add_u64 v[4:5], v[2:3], 0, v[4:5]
	global_store_short v[4:5], v0, off
	ds_read_u16 v0, v48 offset:96
	v_or_b32_e32 v5, 2, v47
	s_waitcnt lgkmcnt(0)
	v_lshlrev_b32_e32 v0, 16, v0
	v_fma_f32 v0, v10, v0, v18
	v_mul_f32_e32 v4, v0, v0
	v_fmamk_f32 v4, v4, 0xbdd2d3e8, v211
	v_mul_f32_e32 v4, v0, v4
	v_exp_f32_e32 v4, v4
	s_nop 0
	v_add_f32_e32 v4, 1.0, v4
	v_rcp_f32_e32 v4, v4
	s_nop 0
	v_mul_f32_e32 v0, v0, v4
	v_or_b32_e32 v4, s1, v5
	v_lshl_add_u32 v5, v5, 6, s0
	v_cndmask_b32_e64 v4, v5, v4, s[36:37]
	v_ashrrev_i32_e32 v5, 31, v4
	v_lshlrev_b64 v[4:5], 9, v[4:5]
	v_cvt_pk_bf16_f32 v0, v0, s0
	v_lshl_add_u64 v[4:5], v[2:3], 0, v[4:5]
	global_store_short v[4:5], v0, off
	ds_read_u16 v0, v48 offset:144
	v_or_b32_e32 v4, 3, v47
	v_or_b32_e32 v5, s1, v4
	v_lshl_add_u32 v4, v4, 6, s0
	v_cndmask_b32_e64 v4, v4, v5, s[36:37]
	s_waitcnt lgkmcnt(0)
	v_lshlrev_b32_e32 v0, 16, v0
	v_fmac_f32_e32 v19, v10, v0
	v_mul_f32_e32 v0, v19, v19
	v_fmamk_f32 v0, v0, 0xbdd2d3e8, v211
	v_mul_f32_e32 v0, v19, v0
	v_exp_f32_e32 v0, v0
	v_ashrrev_i32_e32 v5, 31, v4
	v_lshlrev_b64 v[4:5], 9, v[4:5]
	v_lshl_add_u64 v[4:5], v[2:3], 0, v[4:5]
	v_add_f32_e32 v0, 1.0, v0
	v_rcp_f32_e32 v0, v0
	s_nop 0
	v_mul_f32_e32 v0, v19, v0
	v_cvt_pk_bf16_f32 v0, v0, s0
	global_store_short v[4:5], v0, off
	ds_read_u16 v0, v48 offset:768
	v_or_b32_e32 v5, 16, v47
	s_waitcnt lgkmcnt(0)
	v_lshlrev_b32_e32 v0, 16, v0
	v_fma_f32 v0, v10, v0, v6
	v_mul_f32_e32 v4, v0, v0
	v_fmamk_f32 v4, v4, 0xbdd2d3e8, v211
	v_mul_f32_e32 v4, v0, v4
	v_exp_f32_e32 v4, v4
	s_nop 0
	v_add_f32_e32 v4, 1.0, v4
	v_rcp_f32_e32 v4, v4
	s_nop 0
	v_mul_f32_e32 v0, v0, v4
	v_or_b32_e32 v4, s1, v5
	v_lshl_add_u32 v5, v5, 6, s0
	v_cndmask_b32_e64 v4, v5, v4, s[36:37]
	v_ashrrev_i32_e32 v5, 31, v4
	v_lshlrev_b64 v[4:5], 9, v[4:5]
	v_cvt_pk_bf16_f32 v0, v0, s0
	v_lshl_add_u64 v[4:5], v[2:3], 0, v[4:5]
	global_store_short v[4:5], v0, off
	ds_read_u16 v0, v48 offset:816
	v_or_b32_e32 v5, 17, v47
	s_waitcnt lgkmcnt(0)
	v_lshlrev_b32_e32 v0, 16, v0
	v_fma_f32 v0, v10, v0, v7
	v_mul_f32_e32 v4, v0, v0
	v_fmamk_f32 v4, v4, 0xbdd2d3e8, v211
	v_mul_f32_e32 v4, v0, v4
	v_exp_f32_e32 v4, v4
	s_nop 0
	v_add_f32_e32 v4, 1.0, v4
	v_rcp_f32_e32 v4, v4
	s_nop 0
	v_mul_f32_e32 v0, v0, v4
	v_or_b32_e32 v4, s1, v5
	v_lshl_add_u32 v5, v5, 6, s0
	v_cndmask_b32_e64 v4, v5, v4, s[36:37]
	v_ashrrev_i32_e32 v5, 31, v4
	v_lshlrev_b64 v[4:5], 9, v[4:5]
	v_cvt_pk_bf16_f32 v0, v0, s0
	v_lshl_add_u64 v[4:5], v[2:3], 0, v[4:5]
	global_store_short v[4:5], v0, off
	ds_read_u16 v0, v48 offset:864
	v_or_b32_e32 v5, 18, v47
	s_waitcnt lgkmcnt(0)
	v_lshlrev_b32_e32 v0, 16, v0
	v_fma_f32 v0, v10, v0, v8
	v_mul_f32_e32 v4, v0, v0
	v_fmamk_f32 v4, v4, 0xbdd2d3e8, v211
	v_mul_f32_e32 v4, v0, v4
	v_exp_f32_e32 v4, v4
	s_nop 0
	v_add_f32_e32 v4, 1.0, v4
	v_rcp_f32_e32 v4, v4
	s_nop 0
	v_mul_f32_e32 v0, v0, v4
	v_or_b32_e32 v4, s1, v5
	v_lshl_add_u32 v5, v5, 6, s0
	v_cndmask_b32_e64 v4, v5, v4, s[36:37]
	v_ashrrev_i32_e32 v5, 31, v4
	v_lshlrev_b64 v[4:5], 9, v[4:5]
	v_cvt_pk_bf16_f32 v0, v0, s0
	v_lshl_add_u64 v[4:5], v[2:3], 0, v[4:5]
	global_store_short v[4:5], v0, off
	ds_read_u16 v0, v48 offset:912
	v_or_b32_e32 v4, 19, v47
	v_or_b32_e32 v5, s1, v4
	v_lshl_add_u32 v4, v4, 6, s0
	v_cndmask_b32_e64 v4, v4, v5, s[36:37]
	s_waitcnt lgkmcnt(0)
	v_lshlrev_b32_e32 v0, 16, v0
	v_fmac_f32_e32 v9, v10, v0
	v_mul_f32_e32 v0, v9, v9
	v_fmamk_f32 v0, v0, 0xbdd2d3e8, v211
	v_mul_f32_e32 v0, v9, v0
	v_exp_f32_e32 v0, v0
	v_ashrrev_i32_e32 v5, 31, v4
	v_lshlrev_b64 v[4:5], 9, v[4:5]
	v_lshl_add_u64 v[4:5], v[2:3], 0, v[4:5]
	v_add_f32_e32 v0, 1.0, v0
	v_rcp_f32_e32 v0, v0
	s_nop 0
	v_mul_f32_e32 v0, v9, v0
	v_cvt_pk_bf16_f32 v0, v0, s0
	global_store_short v[4:5], v0, off
	ds_read_u16 v0, v48 offset:1536
	v_or_b32_e32 v5, 32, v47
	s_waitcnt lgkmcnt(0)
	v_lshlrev_b32_e32 v0, 16, v0
	v_fma_f32 v0, v10, v0, v58
	v_mul_f32_e32 v4, v0, v0
	v_fmamk_f32 v4, v4, 0xbdd2d3e8, v211
	v_mul_f32_e32 v4, v0, v4
	v_exp_f32_e32 v4, v4
	s_nop 0
	v_add_f32_e32 v4, 1.0, v4
	v_rcp_f32_e32 v4, v4
	s_nop 0
	v_mul_f32_e32 v0, v0, v4
	v_or_b32_e32 v4, s1, v5
	v_lshl_add_u32 v5, v5, 6, s0
	v_cndmask_b32_e64 v4, v5, v4, s[36:37]
	v_ashrrev_i32_e32 v5, 31, v4
	v_lshlrev_b64 v[4:5], 9, v[4:5]
	v_cvt_pk_bf16_f32 v0, v0, s0
	v_lshl_add_u64 v[4:5], v[2:3], 0, v[4:5]
	global_store_short v[4:5], v0, off
	ds_read_u16 v0, v48 offset:1584
	v_or_b32_e32 v5, 33, v47
	s_waitcnt lgkmcnt(0)
	v_lshlrev_b32_e32 v0, 16, v0
	v_fma_f32 v0, v10, v0, v59
	v_mul_f32_e32 v4, v0, v0
	v_fmamk_f32 v4, v4, 0xbdd2d3e8, v211
	v_mul_f32_e32 v4, v0, v4
	v_exp_f32_e32 v4, v4
	s_nop 0
	v_add_f32_e32 v4, 1.0, v4
	v_rcp_f32_e32 v4, v4
	s_nop 0
	v_mul_f32_e32 v0, v0, v4
	v_or_b32_e32 v4, s1, v5
	v_lshl_add_u32 v5, v5, 6, s0
	v_cndmask_b32_e64 v4, v5, v4, s[36:37]
	v_ashrrev_i32_e32 v5, 31, v4
	v_lshlrev_b64 v[4:5], 9, v[4:5]
	v_cvt_pk_bf16_f32 v0, v0, s0
	v_lshl_add_u64 v[4:5], v[2:3], 0, v[4:5]
	global_store_short v[4:5], v0, off
	ds_read_u16 v0, v48 offset:1632
	v_or_b32_e32 v5, 34, v47
	s_waitcnt lgkmcnt(0)
	v_lshlrev_b32_e32 v0, 16, v0
	v_fma_f32 v0, v10, v0, v60
	v_mul_f32_e32 v4, v0, v0
	v_fmamk_f32 v4, v4, 0xbdd2d3e8, v211
	v_mul_f32_e32 v4, v0, v4
	v_exp_f32_e32 v4, v4
	s_nop 0
	v_add_f32_e32 v4, 1.0, v4
	v_rcp_f32_e32 v4, v4
	s_nop 0
	v_mul_f32_e32 v0, v0, v4
	v_or_b32_e32 v4, s1, v5
	v_lshl_add_u32 v5, v5, 6, s0
	v_cndmask_b32_e64 v4, v5, v4, s[36:37]
	v_ashrrev_i32_e32 v5, 31, v4
	v_lshlrev_b64 v[4:5], 9, v[4:5]
	v_cvt_pk_bf16_f32 v0, v0, s0
	v_lshl_add_u64 v[4:5], v[2:3], 0, v[4:5]
	global_store_short v[4:5], v0, off
	ds_read_u16 v0, v48 offset:1680
	v_or_b32_e32 v4, 35, v47
	v_or_b32_e32 v5, s1, v4
	v_lshl_add_u32 v4, v4, 6, s0
	v_cndmask_b32_e64 v4, v4, v5, s[36:37]
	s_waitcnt lgkmcnt(0)
	v_lshlrev_b32_e32 v0, 16, v0
	v_fmac_f32_e32 v61, v10, v0
	v_mul_f32_e32 v0, v61, v61
	v_fmamk_f32 v0, v0, 0xbdd2d3e8, v211
	v_mul_f32_e32 v0, v61, v0
	v_exp_f32_e32 v0, v0
	v_ashrrev_i32_e32 v5, 31, v4
	v_lshlrev_b64 v[4:5], 9, v[4:5]
	v_lshl_add_u64 v[4:5], v[2:3], 0, v[4:5]
	v_add_f32_e32 v0, 1.0, v0
	v_rcp_f32_e32 v0, v0
	s_nop 0
	v_mul_f32_e32 v0, v61, v0
	v_cvt_pk_bf16_f32 v0, v0, s0
	global_store_short v[4:5], v0, off
	ds_read_u16 v0, v48 offset:2304
	v_or_b32_e32 v5, 48, v47
	s_waitcnt lgkmcnt(0)
	v_lshlrev_b32_e32 v0, 16, v0
	v_fma_f32 v0, v10, v0, v12
	v_mul_f32_e32 v4, v0, v0
	v_fmamk_f32 v4, v4, 0xbdd2d3e8, v211
	v_mul_f32_e32 v4, v0, v4
	v_exp_f32_e32 v4, v4
	s_nop 0
	v_add_f32_e32 v4, 1.0, v4
	v_rcp_f32_e32 v4, v4
	s_nop 0
	v_mul_f32_e32 v0, v0, v4
	v_or_b32_e32 v4, s1, v5
	v_lshl_add_u32 v5, v5, 6, s0
	v_cndmask_b32_e64 v4, v5, v4, s[36:37]
	v_ashrrev_i32_e32 v5, 31, v4
	v_lshlrev_b64 v[4:5], 9, v[4:5]
	v_cvt_pk_bf16_f32 v0, v0, s0
	v_lshl_add_u64 v[4:5], v[2:3], 0, v[4:5]
	global_store_short v[4:5], v0, off
	ds_read_u16 v0, v48 offset:2352
	v_or_b32_e32 v5, 49, v47
	s_waitcnt lgkmcnt(0)
	v_lshlrev_b32_e32 v0, 16, v0
	v_fma_f32 v0, v10, v0, v13
	v_mul_f32_e32 v4, v0, v0
	v_fmamk_f32 v4, v4, 0xbdd2d3e8, v211
	v_mul_f32_e32 v4, v0, v4
	v_exp_f32_e32 v4, v4
	s_nop 0
	v_add_f32_e32 v4, 1.0, v4
	v_rcp_f32_e32 v4, v4
	s_nop 0
	v_mul_f32_e32 v0, v0, v4
	v_or_b32_e32 v4, s1, v5
	v_lshl_add_u32 v5, v5, 6, s0
	v_cndmask_b32_e64 v4, v5, v4, s[36:37]
	v_ashrrev_i32_e32 v5, 31, v4
	v_lshlrev_b64 v[4:5], 9, v[4:5]
	v_cvt_pk_bf16_f32 v0, v0, s0
	v_lshl_add_u64 v[4:5], v[2:3], 0, v[4:5]
	global_store_short v[4:5], v0, off
	ds_read_u16 v0, v48 offset:2400
	v_or_b32_e32 v5, 50, v47
	s_waitcnt lgkmcnt(0)
	v_lshlrev_b32_e32 v0, 16, v0
	v_fma_f32 v0, v10, v0, v14
	v_mul_f32_e32 v4, v0, v0
	v_fmamk_f32 v4, v4, 0xbdd2d3e8, v211
	v_mul_f32_e32 v4, v0, v4
	v_exp_f32_e32 v4, v4
	s_nop 0
	v_add_f32_e32 v4, 1.0, v4
	v_rcp_f32_e32 v4, v4
	s_nop 0
	v_mul_f32_e32 v0, v0, v4
	v_or_b32_e32 v4, s1, v5
	v_lshl_add_u32 v5, v5, 6, s0
	v_cndmask_b32_e64 v4, v5, v4, s[36:37]
	v_ashrrev_i32_e32 v5, 31, v4
	v_lshlrev_b64 v[4:5], 9, v[4:5]
	v_cvt_pk_bf16_f32 v0, v0, s0
	v_lshl_add_u64 v[4:5], v[2:3], 0, v[4:5]
	global_store_short v[4:5], v0, off
	ds_read_u16 v0, v48 offset:2448
	v_or_b32_e32 v4, 51, v47
	v_or_b32_e32 v5, s1, v4
	v_lshl_add_u32 v4, v4, 6, s0
	v_cndmask_b32_e64 v4, v4, v5, s[36:37]
	s_waitcnt lgkmcnt(0)
	v_lshlrev_b32_e32 v0, 16, v0
	v_fmac_f32_e32 v15, v10, v0
	v_mul_f32_e32 v0, v15, v15
	v_fmamk_f32 v0, v0, 0xbdd2d3e8, v211
	v_mul_f32_e32 v0, v15, v0
	v_exp_f32_e32 v0, v0
	v_ashrrev_i32_e32 v5, 31, v4
	v_lshlrev_b64 v[4:5], 9, v[4:5]
	v_lshl_add_u64 v[2:3], v[2:3], 0, v[4:5]
	v_add_f32_e32 v0, 1.0, v0
	v_rcp_f32_e32 v0, v0
	s_nop 0
	v_mul_f32_e32 v0, v15, v0
	v_cvt_pk_bf16_f32 v0, v0, s0
	global_store_short v[2:3], v0, off
	s_waitcnt lgkmcnt(0)
	v_readlane_b32 s0, v244, 24
	s_cmp_lt_i32 s10, s0
	s_cbranch_scc0 .LBB0_296

.LBB0_280:
	s_and_b32 s4, s17, 8
	v_mov_b64_e32 v[4:5], s[0:1]
	s_add_i32 s4, s4, s11
	v_mad_i64_i32 v[2:3], s[0:1], v2, s94, v[4:5]
	s_lshl_b32 s0, s4, 4
	s_ashr_i32 s1, s0, 31
	s_lshr_b32 s5, s6, 6
	v_lshl_add_u64 v[2:3], s[0:1], 1, v[2:3]
	s_mov_b64 s[6:7], 0xe001000
	v_lshl_add_u64 v[6:7], v[2:3], 0, s[6:7]
	v_add_co_u32_e32 v2, vcc, 0xe001000, v2
	s_mulk_i32 s5, 0x3e00
	s_nop 0
	v_addc_co_u32_e32 v3, vcc, 0, v3, vcc
	global_load_dwordx4 v[2:5], v[2:3], off
	s_nop 0
	global_load_dwordx4 v[6:9], v[6:7], off offset:16
	s_add_i32 s5, s5, 0
	v_mad_u32_u24 v0, v0, 48, s5
	v_mov_b32_e32 v62, v204
	s_add_i32 s6, s4, s21
	s_ashr_i32 s7, s6, 31
	s_lshl_b64 s[26:27], s[6:7], 13
	s_waitcnt vmcnt(0) lgkmcnt(0)
	ds_write_b128 v0, v[2:5]
	ds_write_b128 v0, v[6:9] offset:16
	v_mov_b32_e32 v0, s59
	s_waitcnt lgkmcnt(0)
	ds_read_b64 v[2:3], v0
	v_and_b32_e32 v61, 63, v62
	v_readfirstlane_b32 s5, v62
	s_lshr_b32 s5, s5, 6
	s_mulk_i32 s5, 0x3e00
	s_waitcnt lgkmcnt(0)
	v_readfirstlane_b32 s8, v2
	v_lshl_or_b32 v2, s6, 6, v61
	v_readfirstlane_b32 s9, v3
	v_ashrrev_i32_e32 v3, 31, v2
	s_add_i32 s28, s5, 0
	v_lshl_add_u64 v[2:3], v[2:3], 4, s[8:9]
	s_mov_b32 s5, 0x200000
	v_add_co_u32_e32 v2, vcc, s5, v2
	s_add_u32 s26, s8, s26
	v_and_b32_e32 v60, 15, v62
	v_addc_co_u32_e32 v3, vcc, 0, v3, vcc
	s_addc_u32 s27, s9, s27
	v_and_b32_e32 v0, 48, v62
	global_load_dwordx4 v[6:9], v[2:3], off
	v_lshl_add_u64 v[2:3], s[26:27], 0, v[0:1]
	v_lshlrev_b32_e32 v4, 6, v60
	v_mov_b32_e32 v5, v1
	v_lshl_add_u64 v[2:3], v[2:3], 0, v[4:5]
	s_mov_b32 s5, 0x240000
	s_waitcnt vmcnt(0) lgkmcnt(0)
	v_add_co_u32_e32 v8, vcc, s5, v2
	s_mov_b64 s[26:27], 0x240000
	s_nop 0
	v_addc_co_u32_e32 v9, vcc, 0, v3, vcc
	s_mov_b32 s5, 0x241000
	v_lshl_add_u64 v[4:5], v[2:3], 0, s[26:27]
	v_add_co_u32_e32 v2, vcc, s5, v2
	s_lshl_b64 s[6:7], s[6:7], 12
	s_nop 0
	v_addc_co_u32_e32 v3, vcc, 0, v3, vcc
	s_add_u32 s6, s8, s6
	global_load_dwordx4 v[52:55], v[8:9], off
	global_load_dwordx4 v[56:59], v[4:5], off offset:1024
	global_load_dwordx4 v[44:47], v[4:5], off offset:2048
	global_load_dwordx4 v[48:51], v[4:5], off offset:3072
	global_load_dwordx4 v[40:43], v[2:3], off
	global_load_dwordx4 v[36:39], v[2:3], off offset:1024
	global_load_dwordx4 v[32:35], v[2:3], off offset:2048
	global_load_dwordx4 v[28:31], v[2:3], off offset:3072
	s_addc_u32 s7, s9, s7
	v_lshlrev_b32_e32 v2, 8, v60
	v_mov_b32_e32 v3, v1
	v_lshl_add_u64 v[2:3], s[6:7], 0, v[2:3]
	v_lshl_add_u64 v[2:3], v[2:3], 0, v[0:1]
	s_mov_b64 s[6:7], 0x380000
	v_lshl_add_u64 v[4:5], v[2:3], 0, s[6:7]
	s_mov_b32 s5, 0x380000
	s_lshl_b32 s26, s20, 1
	s_mul_i32 s6, s20, 0x88
	s_ashr_i32 s27, s22, 31
	v_add_co_u32_e32 v2, vcc, s5, v2
	s_mul_hi_i32 s5, s26, 0x44
	s_add_u32 s6, s6, s22
	s_addc_u32 s7, s5, s27
	s_ashr_i32 s5, s4, 31
	s_lshl_b64 s[38:39], s[6:7], 10
	s_lshl_b64 s[6:7], s[4:5], 6
	s_add_u32 s5, s38, s6
	v_addc_co_u32_e32 v3, vcc, 0, v3, vcc
	s_addc_u32 s29, s39, s7
	global_load_dwordx4 v[24:27], v[2:3], off
	global_load_dwordx4 v[20:23], v[4:5], off offset:64
	global_load_dwordx4 v[16:19], v[4:5], off offset:128
	global_load_dwordx4 v[12:15], v[4:5], off offset:192
	v_or_b32_e32 v2, s5, v61
	v_mov_b32_e32 v3, s29
	v_lshl_add_u64 v[2:3], v[2:3], 3, s[8:9]
	v_add_co_u32_e32 v2, vcc, 0x1500000, v2
	v_mov_b32_e32 v8, 0
	s_nop 0
	v_addc_co_u32_e32 v3, vcc, 0, v3, vcc
	global_load_dwordx2 v[10:11], v[2:3], off
	v_add_u32_e32 v2, s28, v0
	v_cmp_gt_u32_e32 vcc, 32, v61
	v_mad_u32_u24 v95, v60, 48, v2
	v_mov_b32_e32 v2, 0
	v_mov_b32_e32 v3, 0
	v_mov_b32_e32 v4, 0
	v_mov_b32_e32 v5, 0
	s_and_saveexec_b64 s[8:9], vcc
	ds_read_b128 v[2:5], v95
	s_or_b64 exec, exec, s[8:9]
	s_waitcnt vmcnt(0) lgkmcnt(0)
	v_mfma_f32_16x16x32_bf16 v[64:67], v[2:5], v[52:55], 0
	v_bfe_u32 v9, v62, 4, 2
	v_lshlrev_b32_e32 v79, 2, v61
	v_mov_b32_e32 v61, s28
	v_mfma_f32_16x16x32_bf16 v[70:73], v[2:5], v[56:59], 0
	s_movk_i32 s5, 0x110
	v_lshlrev_b32_e32 v68, 2, v60
	v_mad_u32_u24 v112, v60, s5, v61
	v_mul_u32_u24_e32 v9, 0x840, v9
	v_mfma_f32_16x16x32_bf16 v[60:63], v[2:5], v[44:47], 0
	v_add3_u32 v9, s28, v68, v9
	v_add_u32_e32 v68, 0xc00, v9
	v_add_u32_e32 v69, 0x1000, v9
	v_mfma_f32_16x16x32_bf16 v[74:77], v[2:5], v[48:51], 0
	ds_write2_b32 v68, v64, v70 offset1:16
	ds_write2_b32 v68, v65, v71 offset0:132 offset1:148
	ds_write2_b32 v69, v66, v72 offset0:8 offset1:24
	v_mfma_f32_16x16x32_bf16 v[80:83], v[2:5], v[40:43], 0
	ds_write2_b32 v69, v67, v73 offset0:140 offset1:156
	s_nop 2
	ds_write2_b32 v68, v60, v74 offset0:32 offset1:48
	ds_write2_b32 v68, v61, v75 offset0:164 offset1:180
	v_add_u32_e32 v70, s28, v79
	v_mul_f32_e32 v9, v7, v11
	v_mfma_f32_16x16x32_bf16 v[64:67], v[2:5], v[36:39], 0
	ds_write2_b32 v69, v62, v76 offset0:40 offset1:56
	ds_write2_b32 v69, v63, v77 offset0:172 offset1:188
	s_nop 5
	ds_write2_b32 v68, v80, v64 offset0:64 offset1:80
	ds_write2_b32 v68, v81, v65 offset0:196 offset1:212
	ds_write2_b32 v69, v82, v66 offset0:72 offset1:88
	ds_write2_b32 v69, v83, v67 offset0:204 offset1:220
	v_mfma_f32_16x16x32_bf16 v[60:63], v[2:5], v[32:35], 0
	v_add_u32_e32 v71, 16, v70
	v_fma_f32 v9, v6, v10, -v9
	v_add_u32_e32 v72, 32, v70
	v_mfma_f32_16x16x32_bf16 v[2:5], v[2:5], v[28:31], 0
	s_nop 7
	ds_write2_b32 v68, v60, v2 offset0:96 offset1:112
	ds_write2_b32 v68, v61, v3 offset0:228 offset1:244
	ds_write2_b32 v69, v62, v4 offset0:104 offset1:120
	ds_write2_b32 v69, v63, v5 offset0:236 offset1:252
	s_waitcnt lgkmcnt(0)
	ds_read2st64_b32 v[2:3], v70 offset0:12 offset1:13
	ds_read2st64_b32 v[4:5], v71 offset0:14 offset1:15
	ds_read2st64_b32 v[60:61], v72 offset0:16 offset1:17
	v_add_u32_e32 v87, 0x2c00, v70
	v_add_u32_e32 v73, 48, v70
	s_waitcnt lgkmcnt(2)
	v_add_f32_e32 v2, v9, v2
	v_mul_f32_e32 v9, v7, v10
	v_fmac_f32_e32 v9, v6, v11
	v_add_f32_e32 v3, v9, v3
	v_cvt_pk_bf16_f32 v9, v2, v3
	s_waitcnt lgkmcnt(1)
	v_fma_f32 v10, v7, v2, v5
	v_fma_f32 v4, v6, v2, v4
	v_fma_f32 v4, -v7, v3, v4
	v_fma_f32 v2, v6, v3, v10
	v_cvt_pk_bf16_f32 v3, v4, v2
	ds_write2_b32 v87, v9, v3 offset0:64 offset1:132
	ds_read2st64_b32 v[62:63], v73 offset0:18 offset1:19
	s_waitcnt lgkmcnt(2)
	v_fma_f32 v3, -v2, v7, v60
	v_fma_f32 v2, v2, v6, v61
	v_fma_f32 v2, v4, v7, v2
	v_fma_f32 v3, v4, v6, v3
	v_add_u32_e32 v74, 64, v70
	v_cvt_pk_bf16_f32 v4, v3, v2
	ds_read2st64_b32 v[64:65], v74 offset0:20 offset1:21
	s_waitcnt lgkmcnt(1)
	v_fma_f32 v5, -v2, v7, v62
	v_fma_f32 v2, v2, v6, v63
	v_fma_f32 v2, v3, v7, v2
	v_fma_f32 v5, v3, v6, v5
	v_cvt_pk_bf16_f32 v3, v5, v2
	v_add_u32_e32 v88, 0x2e00, v70
	v_add_u32_e32 v75, 0x50, v70
	ds_write2_b32 v88, v4, v3 offset0:72 offset1:140
	ds_read2st64_b32 v[66:67], v75 offset0:22 offset1:23
	s_waitcnt lgkmcnt(2)
	v_fma_f32 v4, v7, v5, v65
	v_fma_f32 v3, v6, v5, v64
	v_fma_f32 v3, -v7, v2, v3
	v_fma_f32 v2, v6, v2, v4
	v_add_u32_e32 v76, 0x60, v70
	v_cvt_pk_bf16_f32 v4, v3, v2
	ds_read2st64_b32 v[90:91], v76 offset0:24 offset1:25
	s_waitcnt lgkmcnt(1)
	v_fma_f32 v5, -v2, v7, v66
	v_fma_f32 v2, v2, v6, v67
	v_fma_f32 v2, v3, v7, v2
	v_fma_f32 v5, v3, v6, v5
	v_cvt_pk_bf16_f32 v3, v5, v2
	v_add_u32_e32 v89, 0x3000, v70
	v_add_u32_e32 v77, 0x70, v70
	ds_write2_b32 v89, v4, v3 offset0:80 offset1:148
	ds_read2st64_b32 v[92:93], v77 offset0:26 offset1:27
	s_waitcnt lgkmcnt(2)
	v_fma_f32 v4, v7, v5, v91
	v_fma_f32 v3, v6, v5, v90
	v_fma_f32 v3, -v7, v2, v3
	v_fma_f32 v2, v6, v2, v4
	v_add_u32_e32 v79, 0x80, v70
	v_cvt_pk_bf16_f32 v4, v3, v2
	ds_read2st64_b32 v[96:97], v79 offset0:28 offset1:29
	s_waitcnt lgkmcnt(1)
	v_fma_f32 v5, -v2, v7, v92
	v_fma_f32 v2, v2, v6, v93
	v_fma_f32 v2, v3, v7, v2
	v_fma_f32 v5, v3, v6, v5
	v_cvt_pk_bf16_f32 v3, v5, v2
	v_add_u32_e32 v90, 0x3200, v70
	v_add_u32_e32 v80, 0x90, v70
	ds_write2_b32 v90, v4, v3 offset0:88 offset1:156
	ds_read2st64_b32 v[98:99], v80 offset0:30 offset1:31
	s_waitcnt lgkmcnt(2)
	v_fma_f32 v4, v7, v5, v97
	v_fma_f32 v3, v6, v5, v96
	v_fma_f32 v3, -v7, v2, v3
	v_fma_f32 v2, v6, v2, v4
	v_add_u32_e32 v81, 0xa0, v70
	v_cvt_pk_bf16_f32 v4, v3, v2
	ds_read2st64_b32 v[100:101], v81 offset0:32 offset1:33
	s_waitcnt lgkmcnt(1)
	v_fma_f32 v5, -v2, v7, v98
	v_fma_f32 v2, v2, v6, v99
	v_fma_f32 v2, v3, v7, v2
	v_fma_f32 v5, v3, v6, v5
	v_cvt_pk_bf16_f32 v3, v5, v2
	v_add_u32_e32 v91, 0x3400, v70
	v_add_u32_e32 v82, 0xb0, v70
	ds_write2_b32 v91, v4, v3 offset0:96 offset1:164
	ds_read2st64_b32 v[102:103], v82 offset0:34 offset1:35
	s_waitcnt lgkmcnt(2)
	v_fma_f32 v4, v7, v5, v101
	v_fma_f32 v3, v6, v5, v100
	v_fma_f32 v3, -v7, v2, v3
	v_fma_f32 v2, v6, v2, v4
	v_add_u32_e32 v83, 0xc0, v70
	v_cvt_pk_bf16_f32 v4, v3, v2
	ds_read2st64_b32 v[104:105], v83 offset0:36 offset1:37
	s_waitcnt lgkmcnt(1)
	v_fma_f32 v5, -v2, v7, v102
	v_fma_f32 v2, v2, v6, v103
	v_fma_f32 v2, v3, v7, v2
	v_fma_f32 v5, v3, v6, v5
	v_cvt_pk_bf16_f32 v3, v5, v2
	v_add_u32_e32 v92, 0x3600, v70
	v_add_u32_e32 v84, 0xd0, v70
	ds_write2_b32 v92, v4, v3 offset0:104 offset1:172
	ds_read2st64_b32 v[106:107], v84 offset0:38 offset1:39
	s_waitcnt lgkmcnt(2)
	v_fma_f32 v4, v7, v5, v105
	v_fma_f32 v3, v6, v5, v104
	v_fma_f32 v3, -v7, v2, v3
	v_fma_f32 v2, v6, v2, v4
	v_add_u32_e32 v85, 0xe0, v70
	v_cvt_pk_bf16_f32 v4, v3, v2
	ds_read2st64_b32 v[108:109], v85 offset0:40 offset1:41
	s_waitcnt lgkmcnt(1)
	v_fma_f32 v5, -v2, v7, v106
	v_fma_f32 v2, v2, v6, v107
	v_fma_f32 v2, v3, v7, v2
	v_fma_f32 v5, v3, v6, v5
	v_cvt_pk_bf16_f32 v3, v5, v2
	v_add_u32_e32 v93, 0x3800, v70
	v_add_u32_e32 v86, 0xf0, v70
	ds_write2_b32 v93, v4, v3 offset0:112 offset1:180
	ds_read2st64_b32 v[110:111], v86 offset0:42 offset1:43
	s_waitcnt lgkmcnt(2)
	v_fma_f32 v4, v7, v5, v109
	v_fma_f32 v3, v6, v5, v108
	v_fma_f32 v3, -v7, v2, v3
	v_fma_f32 v2, v6, v2, v4
	v_cvt_pk_bf16_f32 v4, v3, v2
	s_waitcnt lgkmcnt(0)
	v_fma_f32 v5, v7, v3, v111
	v_fma_f32 v60, v6, v3, v110
	v_fma_f32 v60, -v7, v2, v60
	v_fma_f32 v61, v6, v2, v5
	v_cvt_pk_bf16_f32 v2, v60, v61
	v_add_u32_e32 v94, 0x3a00, v70
	ds_write2_b32 v94, v4, v2 offset0:120 offset1:188
	s_waitcnt lgkmcnt(0)
	v_add_u32_e32 v0, v112, v0
	ds_read_b128 v[2:5], v0 offset:11520
	ds_read_b128 v[62:65], v0 offset:11584
	s_waitcnt lgkmcnt(1)
	v_mfma_f32_16x16x32_bf16 v[2:5], v[2:5], v[24:27], 0
	ds_read_b128 v[96:99], v0 offset:11648
	v_mov_b32_e32 v9, 0
	v_mov_b32_e32 v10, 0
	s_waitcnt lgkmcnt(1)
	v_mfma_f32_16x16x32_bf16 v[2:5], v[62:65], v[20:23], v[2:5]
	ds_read_b128 v[62:65], v0 offset:11712
	v_mov_b32_e32 v11, 0
	s_waitcnt lgkmcnt(1)
	v_mfma_f32_16x16x32_bf16 v[2:5], v[96:99], v[16:19], v[2:5]
	s_waitcnt lgkmcnt(0)
	v_mfma_f32_16x16x32_bf16 v[2:5], v[62:65], v[12:15], v[2:5]
	s_and_saveexec_b64 s[8:9], vcc
	ds_read_b128 v[8:11], v95 offset:768
	s_or_b64 exec, exec, s[8:9]
	s_waitcnt lgkmcnt(0)
	v_mfma_f32_16x16x32_bf16 v[62:65], v[8:11], v[52:55], 0
	v_mul_f32_e32 v118, v7, v61
	v_fma_f32 v118, v6, v60, -v118
	v_mul_f32_e32 v60, v7, v60
	v_mfma_f32_16x16x32_bf16 v[96:99], v[8:11], v[56:59], 0
	s_nop 7
	ds_write2_b32 v68, v62, v96 offset1:16
	ds_write2_b32 v68, v63, v97 offset0:132 offset1:148
	ds_write2_b32 v69, v64, v98 offset0:8 offset1:24
	v_mfma_f32_16x16x32_bf16 v[100:103], v[8:11], v[44:47], 0
	v_fmac_f32_e32 v60, v6, v61
	v_mfma_f32_16x16x32_bf16 v[104:107], v[8:11], v[48:51], 0
	ds_write2_b32 v69, v65, v99 offset0:140 offset1:156
	s_nop 6
	ds_write2_b32 v68, v100, v104 offset0:32 offset1:48
	ds_write2_b32 v68, v101, v105 offset0:164 offset1:180
	v_mfma_f32_16x16x32_bf16 v[108:111], v[8:11], v[40:43], 0
	v_mfma_f32_16x16x32_bf16 v[62:65], v[8:11], v[36:39], 0
	ds_write2_b32 v69, v102, v106 offset0:40 offset1:56
	ds_write2_b32 v69, v103, v107 offset0:172 offset1:188
	s_nop 5
	ds_write2_b32 v68, v108, v62 offset0:64 offset1:80
	ds_write2_b32 v68, v109, v63 offset0:196 offset1:212
	ds_write2_b32 v69, v110, v64 offset0:72 offset1:88
	ds_write2_b32 v69, v111, v65 offset0:204 offset1:220
	v_mfma_f32_16x16x32_bf16 v[96:99], v[8:11], v[32:35], 0
	v_mfma_f32_16x16x32_bf16 v[8:11], v[8:11], v[28:31], 0
	s_nop 7
	ds_write2_b32 v68, v96, v8 offset0:96 offset1:112
	ds_write2_b32 v68, v97, v9 offset0:228 offset1:244
	ds_write2_b32 v69, v98, v10 offset0:104 offset1:120
	ds_write2_b32 v69, v99, v11 offset0:236 offset1:252
	s_waitcnt lgkmcnt(0)
	ds_read2st64_b32 v[8:9], v70 offset0:12 offset1:13
	ds_read2st64_b32 v[10:11], v71 offset0:14 offset1:15
	ds_read2st64_b32 v[62:63], v72 offset0:16 offset1:17
	ds_read2st64_b32 v[64:65], v73 offset0:18 offset1:19
	ds_read2st64_b32 v[66:67], v74 offset0:20 offset1:21
	ds_read2st64_b32 v[96:97], v75 offset0:22 offset1:23
	ds_read2st64_b32 v[98:99], v76 offset0:24 offset1:25
	ds_read2st64_b32 v[100:101], v77 offset0:26 offset1:27
	ds_read2st64_b32 v[102:103], v79 offset0:28 offset1:29
	ds_read2st64_b32 v[104:105], v80 offset0:30 offset1:31
	ds_read2st64_b32 v[106:107], v81 offset0:32 offset1:33
	ds_read2st64_b32 v[108:109], v82 offset0:34 offset1:35
	ds_read2st64_b32 v[110:111], v83 offset0:36 offset1:37
	ds_read2st64_b32 v[112:113], v84 offset0:38 offset1:39
	ds_read2st64_b32 v[114:115], v85 offset0:40 offset1:41
	ds_read2st64_b32 v[116:117], v86 offset0:42 offset1:43
	s_waitcnt lgkmcnt(14)
	v_add_f32_e32 v8, v118, v8
	v_add_f32_e32 v9, v60, v9
	v_cvt_pk_bf16_f32 v60, v8, v9
	v_fma_f32 v61, v7, v8, v11
	v_fma_f32 v10, v6, v8, v10
	v_fma_f32 v10, -v7, v9, v10
	v_fma_f32 v8, v6, v9, v61
	v_cvt_pk_bf16_f32 v9, v10, v8
	ds_write2_b32 v87, v60, v9 offset0:64 offset1:132
	s_waitcnt lgkmcnt(14)
	v_fma_f32 v9, -v8, v7, v62
	v_fma_f32 v8, v8, v6, v63
	v_fma_f32 v8, v10, v7, v8
	v_fma_f32 v9, v10, v6, v9
	v_cvt_pk_bf16_f32 v10, v9, v8
	s_waitcnt lgkmcnt(13)
	v_fma_f32 v11, -v8, v7, v64
	v_fma_f32 v8, v8, v6, v65
	v_fma_f32 v8, v9, v7, v8
	v_fma_f32 v11, v9, v6, v11
	v_cvt_pk_bf16_f32 v9, v11, v8
	ds_write2_b32 v88, v10, v9 offset0:72 offset1:140
	s_waitcnt lgkmcnt(13)
	v_fma_f32 v10, v7, v11, v67
	v_fma_f32 v9, v6, v11, v66
	v_fma_f32 v9, -v7, v8, v9
	v_fma_f32 v8, v6, v8, v10
	v_cvt_pk_bf16_f32 v10, v9, v8
	s_waitcnt lgkmcnt(12)
	v_fma_f32 v11, -v8, v7, v96
	v_fma_f32 v8, v8, v6, v97
	v_fma_f32 v8, v9, v7, v8
	v_fma_f32 v11, v9, v6, v11
	v_cvt_pk_bf16_f32 v9, v11, v8
	ds_write2_b32 v89, v10, v9 offset0:80 offset1:148
	s_waitcnt lgkmcnt(12)
	v_fma_f32 v10, v7, v11, v99
	v_fma_f32 v9, v6, v11, v98
	v_fma_f32 v9, -v7, v8, v9
	v_fma_f32 v8, v6, v8, v10
	v_cvt_pk_bf16_f32 v10, v9, v8
	s_waitcnt lgkmcnt(11)
	v_fma_f32 v11, -v8, v7, v100
	v_fma_f32 v8, v8, v6, v101
	v_fma_f32 v8, v9, v7, v8
	v_fma_f32 v11, v9, v6, v11
	v_cvt_pk_bf16_f32 v9, v11, v8
	ds_write2_b32 v90, v10, v9 offset0:88 offset1:156
	s_waitcnt lgkmcnt(11)
	v_fma_f32 v10, v7, v11, v103
	v_fma_f32 v9, v6, v11, v102
	v_fma_f32 v9, -v7, v8, v9
	v_fma_f32 v8, v6, v8, v10
	v_cvt_pk_bf16_f32 v10, v9, v8
	s_waitcnt lgkmcnt(10)
	v_fma_f32 v11, -v8, v7, v104
	v_fma_f32 v8, v8, v6, v105
	v_fma_f32 v8, v9, v7, v8
	v_fma_f32 v11, v9, v6, v11
	v_cvt_pk_bf16_f32 v9, v11, v8
	ds_write2_b32 v91, v10, v9 offset0:96 offset1:164
	s_waitcnt lgkmcnt(10)
	v_fma_f32 v10, v7, v11, v107
	v_fma_f32 v9, v6, v11, v106
	v_fma_f32 v9, -v7, v8, v9
	v_fma_f32 v8, v6, v8, v10
	v_cvt_pk_bf16_f32 v10, v9, v8
	s_waitcnt lgkmcnt(9)
	v_fma_f32 v11, -v8, v7, v108
	v_fma_f32 v8, v8, v6, v109
	v_fma_f32 v8, v9, v7, v8
	v_fma_f32 v11, v9, v6, v11
	v_cvt_pk_bf16_f32 v9, v11, v8
	ds_write2_b32 v92, v10, v9 offset0:104 offset1:172
	s_waitcnt lgkmcnt(9)
	v_fma_f32 v10, v7, v11, v111
	v_fma_f32 v9, v6, v11, v110
	v_fma_f32 v9, -v7, v8, v9
	v_fma_f32 v8, v6, v8, v10
	v_cvt_pk_bf16_f32 v10, v9, v8
	s_waitcnt lgkmcnt(8)
	v_fma_f32 v11, -v8, v7, v112
	v_fma_f32 v8, v8, v6, v113
	v_fma_f32 v8, v9, v7, v8
	v_fma_f32 v11, v9, v6, v11
	v_cvt_pk_bf16_f32 v9, v11, v8
	ds_write2_b32 v93, v10, v9 offset0:112 offset1:180
	s_waitcnt lgkmcnt(8)
	v_fma_f32 v10, v7, v11, v115
	v_fma_f32 v9, v6, v11, v114
	v_fma_f32 v9, -v7, v8, v9
	v_fma_f32 v8, v6, v8, v10
	v_cvt_pk_bf16_f32 v10, v9, v8
	s_waitcnt lgkmcnt(7)
	v_fma_f32 v11, v7, v9, v117
	v_fma_f32 v65, v6, v9, v116
	v_fma_f32 v65, -v7, v8, v65
	v_fma_f32 v66, v6, v8, v11
	v_cvt_pk_bf16_f32 v8, v65, v66
	ds_write2_b32 v94, v10, v8 offset0:120 offset1:188
	s_waitcnt lgkmcnt(0)
	ds_read_b128 v[8:11], v0 offset:11520
	ds_read_b128 v[60:63], v0 offset:11584
	s_waitcnt lgkmcnt(1)
	v_mfma_f32_16x16x32_bf16 v[8:11], v[8:11], v[24:27], 0
	ds_read_b128 v[96:99], v0 offset:11648
	v_mov_b32_e32 v64, 0
	s_waitcnt lgkmcnt(1)
	v_mfma_f32_16x16x32_bf16 v[8:11], v[60:63], v[20:23], v[8:11]
	ds_read_b128 v[60:63], v0 offset:11712
	s_waitcnt lgkmcnt(1)
	v_mfma_f32_16x16x32_bf16 v[8:11], v[96:99], v[16:19], v[8:11]
	s_waitcnt lgkmcnt(0)
	v_mfma_f32_16x16x32_bf16 v[8:11], v[60:63], v[12:15], v[8:11]
	v_mov_b32_e32 v60, 0
	v_mov_b32_e32 v61, 0
	v_mov_b32_e32 v62, 0
	v_mov_b32_e32 v63, 0
	s_and_saveexec_b64 s[8:9], vcc
	ds_read_b128 v[60:63], v95 offset:1536
	s_or_b64 exec, exec, s[8:9]
	s_waitcnt lgkmcnt(0)
	v_mfma_f32_16x16x32_bf16 v[96:99], v[60:63], v[52:55], 0
	v_mul_f32_e32 v67, v7, v66
	v_fma_f32 v67, v6, v65, -v67
	v_mul_f32_e32 v65, v7, v65
	v_mfma_f32_16x16x32_bf16 v[100:103], v[60:63], v[56:59], 0
	s_nop 7
	ds_write2_b32 v68, v96, v100 offset1:16
	ds_write2_b32 v68, v97, v101 offset0:132 offset1:148
	ds_write2_b32 v69, v98, v102 offset0:8 offset1:24
	v_mfma_f32_16x16x32_bf16 v[104:107], v[60:63], v[44:47], 0
	v_fmac_f32_e32 v65, v6, v66
	v_mfma_f32_16x16x32_bf16 v[108:111], v[60:63], v[48:51], 0
	ds_write2_b32 v69, v99, v103 offset0:140 offset1:156
	s_nop 6
	ds_write2_b32 v68, v104, v108 offset0:32 offset1:48
	ds_write2_b32 v68, v105, v109 offset0:164 offset1:180
	v_mfma_f32_16x16x32_bf16 v[112:115], v[60:63], v[40:43], 0
	v_mfma_f32_16x16x32_bf16 v[96:99], v[60:63], v[36:39], 0
	ds_write2_b32 v69, v106, v110 offset0:40 offset1:56
	ds_write2_b32 v69, v107, v111 offset0:172 offset1:188
	s_nop 5
	ds_write2_b32 v68, v112, v96 offset0:64 offset1:80
	ds_write2_b32 v68, v113, v97 offset0:196 offset1:212
	ds_write2_b32 v69, v114, v98 offset0:72 offset1:88
	ds_write2_b32 v69, v115, v99 offset0:204 offset1:220
	v_mfma_f32_16x16x32_bf16 v[100:103], v[60:63], v[32:35], 0
	v_mfma_f32_16x16x32_bf16 v[60:63], v[60:63], v[28:31], 0
	s_nop 7
	ds_write2_b32 v68, v100, v60 offset0:96 offset1:112
	ds_write2_b32 v68, v101, v61 offset0:228 offset1:244
	ds_write2_b32 v69, v102, v62 offset0:104 offset1:120
	ds_write2_b32 v69, v103, v63 offset0:236 offset1:252
	s_waitcnt lgkmcnt(0)
	ds_read2st64_b32 v[60:61], v70 offset0:12 offset1:13
	ds_read2st64_b32 v[62:63], v71 offset0:14 offset1:15
	ds_read2st64_b32 v[96:97], v72 offset0:16 offset1:17
	ds_read2st64_b32 v[98:99], v73 offset0:18 offset1:19
	ds_read2st64_b32 v[100:101], v74 offset0:20 offset1:21
	ds_read2st64_b32 v[102:103], v75 offset0:22 offset1:23
	ds_read2st64_b32 v[104:105], v76 offset0:24 offset1:25
	ds_read2st64_b32 v[106:107], v77 offset0:26 offset1:27
	ds_read2st64_b32 v[108:109], v79 offset0:28 offset1:29
	ds_read2st64_b32 v[110:111], v80 offset0:30 offset1:31
	ds_read2st64_b32 v[112:113], v81 offset0:32 offset1:33
	ds_read2st64_b32 v[114:115], v82 offset0:34 offset1:35
	ds_read2st64_b32 v[116:117], v83 offset0:36 offset1:37
	ds_read2st64_b32 v[118:119], v84 offset0:38 offset1:39
	ds_read2st64_b32 v[120:121], v85 offset0:40 offset1:41
	ds_read2st64_b32 v[122:123], v86 offset0:42 offset1:43
	s_waitcnt lgkmcnt(14)
	v_add_f32_e32 v60, v67, v60
	v_add_f32_e32 v61, v65, v61
	v_cvt_pk_bf16_f32 v65, v60, v61
	v_fma_f32 v66, v7, v60, v63
	v_fma_f32 v62, v6, v60, v62
	v_fma_f32 v62, -v7, v61, v62
	v_fma_f32 v60, v6, v61, v66
	v_cvt_pk_bf16_f32 v61, v62, v60
	ds_write2_b32 v87, v65, v61 offset0:64 offset1:132
	s_waitcnt lgkmcnt(14)
	v_fma_f32 v61, -v60, v7, v96
	v_fma_f32 v60, v60, v6, v97
	v_fma_f32 v60, v62, v7, v60
	v_fma_f32 v61, v62, v6, v61
	v_cvt_pk_bf16_f32 v62, v61, v60
	s_waitcnt lgkmcnt(13)
	v_fma_f32 v63, -v60, v7, v98
	v_fma_f32 v60, v60, v6, v99
	v_fma_f32 v60, v61, v7, v60
	v_fma_f32 v63, v61, v6, v63
	v_cvt_pk_bf16_f32 v61, v63, v60
	ds_write2_b32 v88, v62, v61 offset0:72 offset1:140
	s_waitcnt lgkmcnt(13)
	v_fma_f32 v62, v7, v63, v101
	v_fma_f32 v61, v6, v63, v100
	v_fma_f32 v61, -v7, v60, v61
	v_fma_f32 v60, v6, v60, v62
	v_cvt_pk_bf16_f32 v62, v61, v60
	s_waitcnt lgkmcnt(12)
	v_fma_f32 v63, -v60, v7, v102
	v_fma_f32 v60, v60, v6, v103
	v_fma_f32 v60, v61, v7, v60
	v_fma_f32 v63, v61, v6, v63
	v_cvt_pk_bf16_f32 v61, v63, v60
	ds_write2_b32 v89, v62, v61 offset0:80 offset1:148
	s_waitcnt lgkmcnt(12)
	v_fma_f32 v62, v7, v63, v105
	v_fma_f32 v61, v6, v63, v104
	v_fma_f32 v61, -v7, v60, v61
	v_fma_f32 v60, v6, v60, v62
	v_cvt_pk_bf16_f32 v62, v61, v60
	s_waitcnt lgkmcnt(11)
	v_fma_f32 v63, -v60, v7, v106
	v_fma_f32 v60, v60, v6, v107
	v_fma_f32 v60, v61, v7, v60
	v_fma_f32 v63, v61, v6, v63
	v_cvt_pk_bf16_f32 v61, v63, v60
	ds_write2_b32 v90, v62, v61 offset0:88 offset1:156
	s_waitcnt lgkmcnt(11)
	v_fma_f32 v62, v7, v63, v109
	v_fma_f32 v61, v6, v63, v108
	v_fma_f32 v61, -v7, v60, v61
	v_fma_f32 v60, v6, v60, v62
	v_cvt_pk_bf16_f32 v62, v61, v60
	s_waitcnt lgkmcnt(10)
	v_fma_f32 v63, -v60, v7, v110
	v_fma_f32 v60, v60, v6, v111
	v_fma_f32 v60, v61, v7, v60
	v_fma_f32 v63, v61, v6, v63
	v_cvt_pk_bf16_f32 v61, v63, v60
	ds_write2_b32 v91, v62, v61 offset0:96 offset1:164
	s_waitcnt lgkmcnt(10)
	v_fma_f32 v62, v7, v63, v113
	v_fma_f32 v61, v6, v63, v112
	v_fma_f32 v61, -v7, v60, v61
	v_fma_f32 v60, v6, v60, v62
	v_cvt_pk_bf16_f32 v62, v61, v60
	s_waitcnt lgkmcnt(9)
	v_fma_f32 v63, -v60, v7, v114
	v_fma_f32 v60, v60, v6, v115
	v_fma_f32 v60, v61, v7, v60
	v_fma_f32 v63, v61, v6, v63
	v_cvt_pk_bf16_f32 v61, v63, v60
	ds_write2_b32 v92, v62, v61 offset0:104 offset1:172
	s_waitcnt lgkmcnt(9)
	v_fma_f32 v62, v7, v63, v117
	v_fma_f32 v61, v6, v63, v116
	v_fma_f32 v61, -v7, v60, v61
	v_fma_f32 v60, v6, v60, v62
	v_cvt_pk_bf16_f32 v62, v61, v60
	s_waitcnt lgkmcnt(8)
	v_fma_f32 v63, -v60, v7, v118
	v_fma_f32 v60, v60, v6, v119
	v_fma_f32 v60, v61, v7, v60
	v_fma_f32 v63, v61, v6, v63
	v_cvt_pk_bf16_f32 v61, v63, v60
	ds_write2_b32 v93, v62, v61 offset0:112 offset1:180
	s_waitcnt lgkmcnt(8)
	v_fma_f32 v62, v7, v63, v121
	v_fma_f32 v61, v6, v63, v120
	v_fma_f32 v61, -v7, v60, v61
	v_fma_f32 v60, v6, v60, v62
	v_cvt_pk_bf16_f32 v62, v61, v60
	s_waitcnt lgkmcnt(7)
	v_fma_f32 v63, v7, v61, v123
	v_fma_f32 v96, v6, v61, v122
	v_fma_f32 v96, -v7, v60, v96
	v_fma_f32 v97, v6, v60, v63
	v_cvt_pk_bf16_f32 v60, v96, v97
	ds_write2_b32 v94, v62, v60 offset0:120 offset1:188
	s_waitcnt lgkmcnt(0)
	ds_read_b128 v[60:63], v0 offset:11520
	ds_read_b128 v[98:101], v0 offset:11584
	s_waitcnt lgkmcnt(1)
	v_mfma_f32_16x16x32_bf16 v[60:63], v[60:63], v[24:27], 0
	ds_read_b128 v[102:105], v0 offset:11648
	v_mov_b32_e32 v65, 0
	v_mov_b32_e32 v66, 0
	s_waitcnt lgkmcnt(1)
	v_mfma_f32_16x16x32_bf16 v[60:63], v[98:101], v[20:23], v[60:63]
	ds_read_b128 v[98:101], v0 offset:11712
	v_mov_b32_e32 v67, 0
	s_waitcnt lgkmcnt(1)
	v_mfma_f32_16x16x32_bf16 v[60:63], v[102:105], v[16:19], v[60:63]
	s_waitcnt lgkmcnt(0)
	v_mfma_f32_16x16x32_bf16 v[60:63], v[98:101], v[12:15], v[60:63]
	s_and_saveexec_b64 s[8:9], vcc
	ds_read_b128 v[64:67], v95 offset:2304
	s_or_b64 exec, exec, s[8:9]
	s_waitcnt lgkmcnt(0)
	v_mfma_f32_16x16x32_bf16 v[52:55], v[64:67], v[52:55], 0
	s_mov_b32 s9, 0x200000
	v_mfma_f32_16x16x32_bf16 v[56:59], v[64:67], v[56:59], 0
	s_nop 7
	ds_write2_b32 v68, v52, v56 offset1:16
	ds_write2_b32 v68, v53, v57 offset0:132 offset1:148
	ds_write2_b32 v69, v54, v58 offset0:8 offset1:24
	ds_write2_b32 v69, v55, v59 offset0:140 offset1:156
	v_mfma_f32_16x16x32_bf16 v[44:47], v[64:67], v[44:47], 0
	v_mfma_f32_16x16x32_bf16 v[48:51], v[64:67], v[48:51], 0
	s_nop 7
	ds_write2_b32 v68, v44, v48 offset0:32 offset1:48
	ds_write2_b32 v68, v45, v49 offset0:164 offset1:180
	ds_write2_b32 v69, v46, v50 offset0:40 offset1:56
	ds_write2_b32 v69, v47, v51 offset0:172 offset1:188
	v_mfma_f32_16x16x32_bf16 v[40:43], v[64:67], v[40:43], 0
	v_mfma_f32_16x16x32_bf16 v[36:39], v[64:67], v[36:39], 0
	s_nop 7
	ds_write2_b32 v68, v40, v36 offset0:64 offset1:80
	ds_write2_b32 v68, v41, v37 offset0:196 offset1:212
	ds_write2_b32 v69, v42, v38 offset0:72 offset1:88
	ds_write2_b32 v69, v43, v39 offset0:204 offset1:220
	v_mfma_f32_16x16x32_bf16 v[32:35], v[64:67], v[32:35], 0
	v_mfma_f32_16x16x32_bf16 v[28:31], v[64:67], v[28:31], 0
	s_nop 7
	ds_write2_b32 v68, v32, v28 offset0:96 offset1:112
	ds_write2_b32 v68, v33, v29 offset0:228 offset1:244
	ds_write2_b32 v69, v34, v30 offset0:104 offset1:120
	ds_write2_b32 v69, v35, v31 offset0:236 offset1:252
	s_waitcnt lgkmcnt(0)
	v_mul_f32_e32 v64, v7, v97
	ds_read2st64_b32 v[28:29], v70 offset0:12 offset1:13
	ds_read2st64_b32 v[30:31], v71 offset0:14 offset1:15
	ds_read2st64_b32 v[32:33], v72 offset0:16 offset1:17
	ds_read2st64_b32 v[34:35], v73 offset0:18 offset1:19
	ds_read2st64_b32 v[36:37], v74 offset0:20 offset1:21
	ds_read2st64_b32 v[38:39], v75 offset0:22 offset1:23
	ds_read2st64_b32 v[40:41], v76 offset0:24 offset1:25
	ds_read2st64_b32 v[42:43], v77 offset0:26 offset1:27
	ds_read2st64_b32 v[44:45], v79 offset0:28 offset1:29
	ds_read2st64_b32 v[46:47], v80 offset0:30 offset1:31
	ds_read2st64_b32 v[48:49], v81 offset0:32 offset1:33
	ds_read2st64_b32 v[50:51], v82 offset0:34 offset1:35
	ds_read2st64_b32 v[52:53], v83 offset0:36 offset1:37
	ds_read2st64_b32 v[54:55], v84 offset0:38 offset1:39
	ds_read2st64_b32 v[56:57], v85 offset0:40 offset1:41
	ds_read2st64_b32 v[58:59], v86 offset0:42 offset1:43
	v_fma_f32 v64, v6, v96, -v64
	s_waitcnt lgkmcnt(14)
	v_add_f32_e32 v28, v64, v28
	v_mul_f32_e32 v64, v7, v96
	v_fmac_f32_e32 v64, v6, v97
	v_add_f32_e32 v29, v64, v29
	v_cvt_pk_bf16_f32 v64, v28, v29
	v_fma_f32 v65, v7, v28, v31
	v_fma_f32 v30, v6, v28, v30
	v_fma_f32 v30, -v7, v29, v30
	v_fma_f32 v28, v6, v29, v65
	v_cvt_pk_bf16_f32 v29, v30, v28
	ds_write2_b32 v87, v64, v29 offset0:64 offset1:132
	s_waitcnt lgkmcnt(14)
	v_fma_f32 v29, -v28, v7, v32
	v_fma_f32 v28, v28, v6, v33
	v_fma_f32 v28, v30, v7, v28
	v_fma_f32 v29, v30, v6, v29
	v_cvt_pk_bf16_f32 v30, v29, v28
	s_waitcnt lgkmcnt(13)
	v_fma_f32 v31, -v28, v7, v34
	v_fma_f32 v28, v28, v6, v35
	v_fma_f32 v28, v29, v7, v28
	v_fma_f32 v31, v29, v6, v31
	v_cvt_pk_bf16_f32 v29, v31, v28
	ds_write2_b32 v88, v30, v29 offset0:72 offset1:140
	s_waitcnt lgkmcnt(13)
	v_fma_f32 v30, v7, v31, v37
	v_fma_f32 v29, v6, v31, v36
	v_fma_f32 v29, -v7, v28, v29
	v_fma_f32 v28, v6, v28, v30
	v_cvt_pk_bf16_f32 v30, v29, v28
	s_waitcnt lgkmcnt(12)
	v_fma_f32 v31, -v28, v7, v38
	v_fma_f32 v28, v28, v6, v39
	v_fma_f32 v28, v29, v7, v28
	v_fma_f32 v31, v29, v6, v31
	v_cvt_pk_bf16_f32 v29, v31, v28
	ds_write2_b32 v89, v30, v29 offset0:80 offset1:148
	s_waitcnt lgkmcnt(12)
	v_fma_f32 v30, v7, v31, v41
	v_fma_f32 v29, v6, v31, v40
	v_fma_f32 v29, -v7, v28, v29
	v_fma_f32 v28, v6, v28, v30
	v_cvt_pk_bf16_f32 v30, v29, v28
	s_waitcnt lgkmcnt(11)
	v_fma_f32 v31, -v28, v7, v42
	v_fma_f32 v28, v28, v6, v43
	v_fma_f32 v28, v29, v7, v28
	v_fma_f32 v31, v29, v6, v31
	v_cvt_pk_bf16_f32 v29, v31, v28
	ds_write2_b32 v90, v30, v29 offset0:88 offset1:156
	s_waitcnt lgkmcnt(11)
	v_fma_f32 v30, v7, v31, v45
	v_fma_f32 v29, v6, v31, v44
	v_fma_f32 v29, -v7, v28, v29
	v_fma_f32 v28, v6, v28, v30
	v_cvt_pk_bf16_f32 v30, v29, v28
	s_waitcnt lgkmcnt(10)
	v_fma_f32 v31, -v28, v7, v46
	v_fma_f32 v28, v28, v6, v47
	v_fma_f32 v28, v29, v7, v28
	v_fma_f32 v31, v29, v6, v31
	v_cvt_pk_bf16_f32 v29, v31, v28
	ds_write2_b32 v91, v30, v29 offset0:96 offset1:164
	s_waitcnt lgkmcnt(10)
	v_fma_f32 v30, v7, v31, v49
	v_fma_f32 v29, v6, v31, v48
	v_fma_f32 v29, -v7, v28, v29
	v_fma_f32 v28, v6, v28, v30
	v_cvt_pk_bf16_f32 v30, v29, v28
	s_waitcnt lgkmcnt(9)
	v_fma_f32 v31, -v28, v7, v50
	v_fma_f32 v28, v28, v6, v51
	v_fma_f32 v28, v29, v7, v28
	v_fma_f32 v31, v29, v6, v31
	v_cvt_pk_bf16_f32 v29, v31, v28
	ds_write2_b32 v92, v30, v29 offset0:104 offset1:172
	s_waitcnt lgkmcnt(9)
	v_fma_f32 v30, v7, v31, v53
	v_fma_f32 v29, v6, v31, v52
	v_fma_f32 v29, -v7, v28, v29
	v_fma_f32 v28, v6, v28, v30
	v_cvt_pk_bf16_f32 v30, v29, v28
	s_waitcnt lgkmcnt(8)
	v_fma_f32 v31, -v28, v7, v54
	v_fma_f32 v28, v28, v6, v55
	v_fma_f32 v28, v29, v7, v28
	v_fma_f32 v31, v29, v6, v31
	v_cvt_pk_bf16_f32 v29, v31, v28
	ds_write2_b32 v93, v30, v29 offset0:112 offset1:180
	s_waitcnt lgkmcnt(8)
	v_fma_f32 v30, v7, v31, v57
	v_fma_f32 v29, v6, v31, v56
	v_fma_f32 v29, -v7, v28, v29
	v_fma_f32 v28, v6, v28, v30
	v_mul_f32_e32 v31, v7, v28
	v_mul_f32_e32 v7, v7, v29
	v_fma_f32 v31, v6, v29, -v31
	v_fmac_f32_e32 v7, v6, v28
	s_waitcnt lgkmcnt(7)
	v_add_f32_e32 v31, v58, v31
	v_add_f32_e32 v6, v59, v7
	v_cvt_pk_bf16_f32 v30, v29, v28
	v_cvt_pk_bf16_f32 v6, v31, v6
	ds_write2_b32 v94, v30, v6 offset0:120 offset1:188
	s_waitcnt lgkmcnt(0)
	ds_read_b128 v[28:31], v0 offset:11520
	s_waitcnt lgkmcnt(0)
	v_mfma_f32_16x16x32_bf16 v[24:27], v[28:31], v[24:27], 0
	ds_read_b128 v[28:31], v0 offset:11584
	v_mov_b32_e32 v73, v204
	v_mov_b32_e32 v72, 0
	s_waitcnt lgkmcnt(0)
	v_mfma_f32_16x16x32_bf16 v[20:23], v[28:31], v[20:23], v[24:27]
	s_nop 2
	ds_read_b128 v[24:27], v0 offset:11648
	v_mov_b32_e32 v75, 0
	v_mov_b32_e32 v76, 0
	s_waitcnt lgkmcnt(0)
	v_mfma_f32_16x16x32_bf16 v[16:19], v[24:27], v[16:19], v[20:23]
	s_nop 2
	ds_read_b128 v[20:23], v0 offset:11712
	v_mov_b32_e32 v0, s59
	ds_read_b64 v[6:7], v0
	v_readfirstlane_b32 s5, v73
	s_lshr_b32 s5, s5, 6
	s_mulk_i32 s5, 0x3e00
	s_add_i32 s8, s5, 0
	v_readlane_b32 s5, v244, 25
	v_and_b32_e32 v59, 63, v73
	s_add_i32 s28, s4, s5
	s_waitcnt lgkmcnt(0)
	v_readfirstlane_b32 s4, v6
	v_lshl_or_b32 v6, s28, 6, v59
	v_readfirstlane_b32 s5, v7
	v_ashrrev_i32_e32 v7, 31, v6
	s_ashr_i32 s29, s28, 31
	v_lshl_add_u64 v[6:7], v[6:7], 4, s[4:5]
	s_lshl_b64 s[38:39], s[28:29], 13
	v_add_co_u32_e32 v6, vcc, s9, v6
	s_add_u32 s38, s4, s38
	v_and_b32_e32 v58, 15, v73
	v_addc_co_u32_e32 v7, vcc, 0, v7, vcc
	s_addc_u32 s39, s5, s39
	v_and_b32_e32 v0, 48, v73
	v_mfma_f32_16x16x32_bf16 v[12:15], v[20:23], v[12:15], v[16:19]
	global_load_dwordx4 v[32:35], v[6:7], off
	v_lshl_add_u64 v[6:7], s[38:39], 0, v[0:1]
	s_mov_b32 s9, 0x240000
	v_lshlrev_b32_e32 v16, 6, v58
	v_mov_b32_e32 v17, v1
	v_lshl_add_u64 v[6:7], v[6:7], 0, v[16:17]
	v_add_co_u32_e32 v18, vcc, s9, v6
	s_mov_b64 s[38:39], 0x240000
	s_nop 0
	v_addc_co_u32_e32 v19, vcc, 0, v7, vcc
	s_mov_b32 s9, 0x241000
	v_lshl_add_u64 v[16:17], v[6:7], 0, s[38:39]
	v_add_co_u32_e32 v6, vcc, s9, v6
	s_lshl_b64 s[28:29], s[28:29], 12
	s_nop 0
	v_addc_co_u32_e32 v7, vcc, 0, v7, vcc
	s_add_u32 s28, s4, s28
	global_load_dwordx4 v[42:45], v[18:19], off
	global_load_dwordx4 v[68:71], v[16:17], off offset:1024
	global_load_dwordx4 v[64:67], v[16:17], off offset:2048
	global_load_dwordx4 v[50:53], v[16:17], off offset:3072
	global_load_dwordx4 v[54:57], v[6:7], off
	global_load_dwordx4 v[46:49], v[6:7], off offset:1024
	global_load_dwordx4 v[38:41], v[6:7], off offset:2048
	s_waitcnt vmcnt(0) lgkmcnt(0)
	global_load_dwordx4 v[34:37], v[6:7], off offset:3072
	s_addc_u32 s29, s5, s29
	v_lshlrev_b32_e32 v6, 8, v58
	v_mov_b32_e32 v7, v1
	v_lshl_add_u64 v[6:7], s[28:29], 0, v[6:7]
	v_lshl_add_u64 v[6:7], v[6:7], 0, v[0:1]
	s_mov_b64 s[28:29], 0x380000
	s_mov_b32 s9, 0x380000
	v_lshl_add_u64 v[16:17], v[6:7], 0, s[28:29]
	v_add_co_u32_e32 v6, vcc, s9, v6
	s_or_b32 s9, s26, 1
	s_mul_hi_i32 s28, s9, 0x44
	s_mulk_i32 s9, 0x44
	s_add_u32 s26, s9, s22
	s_addc_u32 s27, s28, s27
	s_lshl_b64 s[26:27], s[26:27], 10
	s_add_u32 s6, s26, s6
	v_addc_co_u32_e32 v7, vcc, 0, v7, vcc
	s_addc_u32 s7, s27, s7
	global_load_dwordx4 v[20:23], v[6:7], off
	global_load_dwordx4 v[28:31], v[16:17], off offset:64
	global_load_dwordx4 v[24:27], v[16:17], off offset:128
	s_nop 0
	global_load_dwordx4 v[16:19], v[16:17], off offset:192
	v_or_b32_e32 v6, s6, v59
	v_mov_b32_e32 v7, s7
	v_lshl_add_u64 v[6:7], v[6:7], 3, s[4:5]
	v_add_co_u32_e32 v6, vcc, 0x1500000, v6
	v_add_u32_e32 v74, s8, v0
	s_nop 0
	v_addc_co_u32_e32 v7, vcc, 0, v7, vcc
	global_load_dwordx2 v[6:7], v[6:7], off
	v_cmp_gt_u32_e32 vcc, 32, v59
	v_mad_u32_u24 v81, v58, 48, v74
	v_mov_b32_e32 v74, 0
	v_mov_b32_e32 v77, 0
	s_and_saveexec_b64 s[4:5], vcc
	ds_read_b128 v[74:77], v81 offset:2304
	s_or_b64 exec, exec, s[4:5]
	s_waitcnt lgkmcnt(0)
	v_mfma_f32_16x16x32_bf16 v[82:85], v[74:77], v[42:45], 0
	v_bfe_u32 v73, v73, 4, 2
	v_mov_b32_e32 v80, s8
	s_movk_i32 s4, 0x110
	v_mfma_f32_16x16x32_bf16 v[86:89], v[74:77], v[68:71], 0
	v_lshlrev_b32_e32 v79, 2, v58
	v_mad_u32_u24 v126, v58, s4, v80
	v_mul_u32_u24_e32 v58, 0x840, v73
	v_mfma_f32_16x16x32_bf16 v[90:93], v[74:77], v[64:67], 0
	v_add3_u32 v58, s8, v79, v58
	v_add_u32_e32 v80, 0xc00, v58
	s_nop 1
	ds_write2_b32 v80, v82, v86 offset1:16
	v_mfma_f32_16x16x32_bf16 v[94:97], v[74:77], v[50:53], 0
	v_add_u32_e32 v82, 0x1000, v58
	ds_write2_b32 v80, v83, v87 offset0:132 offset1:148
	ds_write2_b32 v82, v84, v88 offset0:8 offset1:24
	v_mfma_f32_16x16x32_bf16 v[98:101], v[74:77], v[54:57], 0
	ds_write2_b32 v82, v85, v89 offset0:140 offset1:156
	s_nop 2
	ds_write2_b32 v80, v90, v94 offset0:32 offset1:48
	ds_write2_b32 v80, v91, v95 offset0:164 offset1:180
	v_lshlrev_b32_e32 v59, 2, v59
	v_add_u32_e32 v83, s8, v59
	v_mfma_f32_16x16x32_bf16 v[84:87], v[74:77], v[46:49], 0
	ds_write2_b32 v82, v92, v96 offset0:40 offset1:56
	ds_write2_b32 v82, v93, v97 offset0:172 offset1:188
	s_nop 5
	ds_write2_b32 v80, v98, v84 offset0:64 offset1:80
	ds_write2_b32 v80, v99, v85 offset0:196 offset1:212
	ds_write2_b32 v82, v100, v86 offset0:72 offset1:88
	ds_write2_b32 v82, v101, v87 offset0:204 offset1:220
	v_mfma_f32_16x16x32_bf16 v[88:91], v[74:77], v[38:41], 0
	v_add_u32_e32 v84, 0xf0, v83
	v_add_u32_e32 v85, 0xe0, v83
	s_waitcnt vmcnt(0)
	v_mul_f32_e32 v73, v33, v7
	v_mfma_f32_16x16x32_bf16 v[74:77], v[74:77], v[34:37], 0
	s_nop 7
	ds_write2_b32 v80, v88, v74 offset0:96 offset1:112
	ds_write2_b32 v80, v89, v75 offset0:228 offset1:244
	ds_write2_b32 v82, v90, v76 offset0:104 offset1:120
	ds_write2_b32 v82, v91, v77 offset0:236 offset1:252
	s_waitcnt lgkmcnt(0)
	ds_read2st64_b32 v[58:59], v84 offset0:42 offset1:43
	ds_read2st64_b32 v[74:75], v85 offset0:40 offset1:41
	v_fma_f32 v73, v32, v6, -v73
	v_mul_f32_e32 v6, v33, v6
	v_fmac_f32_e32 v6, v32, v7
	s_waitcnt lgkmcnt(1)
	v_add_f32_e32 v58, v73, v58
	v_add_f32_e32 v6, v6, v59
	v_add_u32_e32 v86, 0xd0, v83
	v_cvt_pk_bf16_f32 v7, v58, v6
	ds_read2st64_b32 v[76:77], v86 offset0:38 offset1:39
	s_waitcnt lgkmcnt(1)
	v_fma_f32 v59, -v6, v33, v74
	v_fma_f32 v6, v6, v32, v75
	v_fma_f32 v6, v58, v33, v6
	v_fma_f32 v59, v58, v32, v59
	v_add_u32_e32 v87, 0xc0, v83
	v_add_u32_e32 v88, 0xb0, v83
	v_add_u32_e32 v89, 0xa0, v83
	v_add_u32_e32 v90, 0x90, v83
	v_add_u32_e32 v91, 0x80, v83
	v_add_u32_e32 v92, 0x70, v83
	v_add_u32_e32 v93, 0x60, v83
	v_add_u32_e32 v94, 0x50, v83
	v_add_u32_e32 v95, 64, v83
	v_add_u32_e32 v96, 48, v83
	v_add_u32_e32 v97, 32, v83
	v_add_u32_e32 v98, 16, v83
	v_cvt_pk_bf16_f32 v58, v59, v6
	v_add_u32_e32 v99, 0x3a00, v83
	ds_read2st64_b32 v[100:101], v87 offset0:36 offset1:37
	ds_read2st64_b32 v[102:103], v88 offset0:34 offset1:35
	ds_read2st64_b32 v[104:105], v89 offset0:32 offset1:33
	ds_read2st64_b32 v[106:107], v90 offset0:30 offset1:31
	ds_read2st64_b32 v[108:109], v91 offset0:28 offset1:29
	ds_read2st64_b32 v[110:111], v92 offset0:26 offset1:27
	ds_read2st64_b32 v[112:113], v93 offset0:24 offset1:25
	ds_read2st64_b32 v[114:115], v94 offset0:22 offset1:23
	ds_read2st64_b32 v[116:117], v95 offset0:20 offset1:21
	ds_read2st64_b32 v[118:119], v96 offset0:18 offset1:19
	ds_read2st64_b32 v[120:121], v97 offset0:16 offset1:17
	ds_read2st64_b32 v[122:123], v98 offset0:14 offset1:15
	ds_read2st64_b32 v[124:125], v83 offset0:12 offset1:13
	ds_write2_b32 v99, v58, v7 offset0:120 offset1:188
	s_waitcnt lgkmcnt(14)
	v_fma_f32 v58, v33, v59, v77
	v_fma_f32 v7, v32, v59, v76
	v_fma_f32 v7, -v33, v6, v7
	v_fma_f32 v6, v32, v6, v58
	v_cvt_pk_bf16_f32 v58, v7, v6
	s_waitcnt lgkmcnt(13)
	v_fma_f32 v59, -v6, v33, v100
	v_fma_f32 v6, v6, v32, v101
	v_fma_f32 v6, v7, v33, v6
	v_fma_f32 v59, v7, v32, v59
	v_cvt_pk_bf16_f32 v7, v59, v6
	v_add_u32_e32 v100, 0x3800, v83
	ds_write2_b32 v100, v7, v58 offset0:112 offset1:180
	s_waitcnt lgkmcnt(13)
	v_fma_f32 v58, v33, v59, v103
	v_fma_f32 v7, v32, v59, v102
	v_fma_f32 v7, -v33, v6, v7
	v_fma_f32 v6, v32, v6, v58
	v_cvt_pk_bf16_f32 v58, v7, v6
	s_waitcnt lgkmcnt(12)
	v_fma_f32 v59, -v6, v33, v104
	v_fma_f32 v6, v6, v32, v105
	v_fma_f32 v6, v7, v33, v6
	v_fma_f32 v59, v7, v32, v59
	v_cvt_pk_bf16_f32 v7, v59, v6
	v_add_u32_e32 v101, 0x3600, v83
	ds_write2_b32 v101, v7, v58 offset0:104 offset1:172
	s_waitcnt lgkmcnt(12)
	v_fma_f32 v58, v33, v59, v107
	v_fma_f32 v7, v32, v59, v106
	v_fma_f32 v7, -v33, v6, v7
	v_fma_f32 v6, v32, v6, v58
	v_cvt_pk_bf16_f32 v58, v7, v6
	s_waitcnt lgkmcnt(11)
	v_fma_f32 v59, -v6, v33, v108
	v_fma_f32 v6, v6, v32, v109
	v_fma_f32 v6, v7, v33, v6
	v_fma_f32 v59, v7, v32, v59
	v_cvt_pk_bf16_f32 v7, v59, v6
	v_add_u32_e32 v102, 0x3400, v83
	ds_write2_b32 v102, v7, v58 offset0:96 offset1:164
	s_waitcnt lgkmcnt(11)
	v_fma_f32 v58, v33, v59, v111
	v_fma_f32 v7, v32, v59, v110
	v_fma_f32 v7, -v33, v6, v7
	v_fma_f32 v6, v32, v6, v58
	v_cvt_pk_bf16_f32 v58, v7, v6
	s_waitcnt lgkmcnt(10)
	v_fma_f32 v59, -v6, v33, v112
	v_fma_f32 v6, v6, v32, v113
	v_fma_f32 v6, v7, v33, v6
	v_fma_f32 v59, v7, v32, v59
	v_cvt_pk_bf16_f32 v7, v59, v6
	v_add_u32_e32 v103, 0x3200, v83
	ds_write2_b32 v103, v7, v58 offset0:88 offset1:156
	s_waitcnt lgkmcnt(10)
	v_fma_f32 v58, v33, v59, v115
	v_fma_f32 v7, v32, v59, v114
	v_fma_f32 v7, -v33, v6, v7
	v_fma_f32 v6, v32, v6, v58
	v_cvt_pk_bf16_f32 v58, v7, v6
	s_waitcnt lgkmcnt(9)
	v_fma_f32 v59, -v6, v33, v116
	v_fma_f32 v6, v6, v32, v117
	v_fma_f32 v6, v7, v33, v6
	v_fma_f32 v59, v7, v32, v59
	v_cvt_pk_bf16_f32 v7, v59, v6
	v_add_u32_e32 v104, 0x3000, v83
	ds_write2_b32 v104, v7, v58 offset0:80 offset1:148
	s_waitcnt lgkmcnt(9)
	v_fma_f32 v58, v33, v59, v119
	v_fma_f32 v7, v32, v59, v118
	v_fma_f32 v7, -v33, v6, v7
	v_fma_f32 v6, v32, v6, v58
	v_cvt_pk_bf16_f32 v58, v7, v6
	s_waitcnt lgkmcnt(8)
	v_fma_f32 v59, -v6, v33, v120
	v_fma_f32 v6, v6, v32, v121
	v_fma_f32 v6, v7, v33, v6
	v_fma_f32 v59, v7, v32, v59
	v_cvt_pk_bf16_f32 v7, v59, v6
	v_add_u32_e32 v105, 0x2e00, v83
	ds_write2_b32 v105, v7, v58 offset0:72 offset1:140
	s_waitcnt lgkmcnt(8)
	v_fma_f32 v58, v33, v59, v123
	v_fma_f32 v7, v32, v59, v122
	v_fma_f32 v7, -v33, v6, v7
	v_fma_f32 v58, v32, v6, v58
	v_mul_f32_e32 v6, v33, v58
	v_cvt_pk_bf16_f32 v59, v7, v58
	v_fma_f32 v6, v32, v7, -v6
	v_mul_f32_e32 v7, v33, v7
	v_fmac_f32_e32 v7, v32, v58
	s_waitcnt lgkmcnt(7)
	v_add_f32_e32 v6, v124, v6
	v_add_f32_e32 v7, v125, v7
	v_cvt_pk_bf16_f32 v58, v6, v7
	v_add_u32_e32 v106, 0x2c00, v83
	ds_write2_b32 v106, v58, v59 offset0:64 offset1:132
	s_waitcnt lgkmcnt(0)
	v_add_u32_e32 v79, v126, v0
	ds_read_b128 v[74:77], v79 offset:11520
	ds_read_b128 v[108:111], v79 offset:11584
	s_waitcnt lgkmcnt(1)
	v_mfma_f32_16x16x32_bf16 v[12:15], v[74:77], v[20:23], v[12:15]
	ds_read_b128 v[74:77], v79 offset:11648
	v_mov_b32_e32 v73, 0
	s_waitcnt lgkmcnt(1)
	v_mfma_f32_16x16x32_bf16 v[12:15], v[108:111], v[28:31], v[12:15]
	ds_read_b128 v[108:111], v79 offset:11712
	s_waitcnt lgkmcnt(1)
	v_mfma_f32_16x16x32_bf16 v[12:15], v[74:77], v[24:27], v[12:15]
	v_mov_b32_e32 v74, 0
	v_mov_b32_e32 v75, 0
	s_waitcnt lgkmcnt(0)
	v_mfma_f32_16x16x32_bf16 v[12:15], v[108:111], v[16:19], v[12:15]
	s_and_saveexec_b64 s[4:5], vcc
	ds_read_b128 v[72:75], v81 offset:1536
	s_or_b64 exec, exec, s[4:5]
	s_waitcnt lgkmcnt(0)
	v_mfma_f32_16x16x32_bf16 v[108:111], v[72:75], v[42:45], 0
	v_mul_f32_e32 v0, v33, v7
	v_fma_f32 v0, v32, v6, -v0
	v_mul_f32_e32 v6, v33, v6
	v_mfma_f32_16x16x32_bf16 v[112:115], v[72:75], v[68:71], 0
	s_nop 7
	ds_write2_b32 v80, v108, v112 offset1:16
	ds_write2_b32 v80, v109, v113 offset0:132 offset1:148
	ds_write2_b32 v82, v110, v114 offset0:8 offset1:24
	v_mfma_f32_16x16x32_bf16 v[116:119], v[72:75], v[64:67], 0
	v_fmac_f32_e32 v6, v32, v7
	v_mfma_f32_16x16x32_bf16 v[120:123], v[72:75], v[50:53], 0
	ds_write2_b32 v82, v111, v115 offset0:140 offset1:156
	s_nop 6
	ds_write2_b32 v80, v116, v120 offset0:32 offset1:48
	ds_write2_b32 v80, v117, v121 offset0:164 offset1:180
	v_mfma_f32_16x16x32_bf16 v[124:127], v[72:75], v[54:57], 0
	v_mfma_f32_16x16x32_bf16 v[108:111], v[72:75], v[46:49], 0
	ds_write2_b32 v82, v118, v122 offset0:40 offset1:56
	ds_write2_b32 v82, v119, v123 offset0:172 offset1:188
	s_nop 5
	ds_write2_b32 v80, v124, v108 offset0:64 offset1:80
	ds_write2_b32 v80, v125, v109 offset0:196 offset1:212
	ds_write2_b32 v82, v126, v110 offset0:72 offset1:88
	ds_write2_b32 v82, v127, v111 offset0:204 offset1:220
	v_mfma_f32_16x16x32_bf16 v[112:115], v[72:75], v[38:41], 0
	v_mfma_f32_16x16x32_bf16 v[72:75], v[72:75], v[34:37], 0
	s_nop 7
	ds_write2_b32 v80, v112, v72 offset0:96 offset1:112
	ds_write2_b32 v80, v113, v73 offset0:228 offset1:244
	ds_write2_b32 v82, v114, v74 offset0:104 offset1:120
	ds_write2_b32 v82, v115, v75 offset0:236 offset1:252
	s_waitcnt lgkmcnt(0)
	ds_read2st64_b32 v[58:59], v84 offset0:42 offset1:43
	ds_read2st64_b32 v[72:73], v85 offset0:40 offset1:41
	ds_read2st64_b32 v[74:75], v86 offset0:38 offset1:39
	ds_read2st64_b32 v[76:77], v87 offset0:36 offset1:37
	ds_read2st64_b32 v[108:109], v88 offset0:34 offset1:35
	ds_read2st64_b32 v[110:111], v89 offset0:32 offset1:33
	ds_read2st64_b32 v[112:113], v90 offset0:30 offset1:31
	ds_read2st64_b32 v[114:115], v91 offset0:28 offset1:29
	ds_read2st64_b32 v[116:117], v92 offset0:26 offset1:27
	ds_read2st64_b32 v[118:119], v93 offset0:24 offset1:25
	ds_read2st64_b32 v[120:121], v94 offset0:22 offset1:23
	ds_read2st64_b32 v[122:123], v95 offset0:20 offset1:21
	ds_read2st64_b32 v[124:125], v96 offset0:18 offset1:19
	ds_read2st64_b32 v[126:127], v97 offset0:16 offset1:17
	ds_read2st64_b32 v[128:129], v98 offset0:14 offset1:15
	ds_read2st64_b32 v[130:131], v83 offset0:12 offset1:13
	s_waitcnt lgkmcnt(14)
	v_add_f32_e32 v0, v0, v58
	v_add_f32_e32 v6, v6, v59
	v_cvt_pk_bf16_f32 v7, v0, v6
	v_mul_f32_e32 v58, v33, v6
	v_mul_f32_e32 v6, v32, v6
	v_fma_f32 v58, v32, v0, -v58
	v_fmac_f32_e32 v6, v33, v0
	v_add_f32_e32 v58, v72, v58
	v_add_f32_e32 v0, v73, v6
	v_cvt_pk_bf16_f32 v6, v58, v0
	ds_write2_b32 v99, v6, v7 offset0:120 offset1:188
	s_waitcnt lgkmcnt(14)
	v_fma_f32 v7, v33, v58, v75
	v_fma_f32 v6, v32, v58, v74
	v_fma_f32 v6, -v33, v0, v6
	v_fma_f32 v0, v32, v0, v7
	v_cvt_pk_bf16_f32 v7, v6, v0
	s_waitcnt lgkmcnt(13)
	v_fma_f32 v58, -v0, v33, v76
	v_fma_f32 v0, v0, v32, v77
	v_fma_f32 v0, v6, v33, v0
	v_fma_f32 v58, v6, v32, v58
	v_cvt_pk_bf16_f32 v6, v58, v0
	ds_write2_b32 v100, v6, v7 offset0:112 offset1:180
	s_waitcnt lgkmcnt(13)
	v_fma_f32 v7, v33, v58, v109
	v_fma_f32 v6, v32, v58, v108
	v_fma_f32 v6, -v33, v0, v6
	v_fma_f32 v0, v32, v0, v7
	v_cvt_pk_bf16_f32 v7, v6, v0
	s_waitcnt lgkmcnt(12)
	v_fma_f32 v58, -v0, v33, v110
	v_fma_f32 v0, v0, v32, v111
	v_fma_f32 v0, v6, v33, v0
	v_fma_f32 v58, v6, v32, v58
	v_cvt_pk_bf16_f32 v6, v58, v0
	ds_write2_b32 v101, v6, v7 offset0:104 offset1:172
	s_waitcnt lgkmcnt(12)
	v_fma_f32 v7, v33, v58, v113
	v_fma_f32 v6, v32, v58, v112
	v_fma_f32 v6, -v33, v0, v6
	v_fma_f32 v0, v32, v0, v7
	v_cvt_pk_bf16_f32 v7, v6, v0
	s_waitcnt lgkmcnt(11)
	v_fma_f32 v58, -v0, v33, v114
	v_fma_f32 v0, v0, v32, v115
	v_fma_f32 v0, v6, v33, v0
	v_fma_f32 v58, v6, v32, v58
	v_cvt_pk_bf16_f32 v6, v58, v0
	ds_write2_b32 v102, v6, v7 offset0:96 offset1:164
	s_waitcnt lgkmcnt(11)
	v_fma_f32 v7, v33, v58, v117
	v_fma_f32 v6, v32, v58, v116
	v_fma_f32 v6, -v33, v0, v6
	v_fma_f32 v0, v32, v0, v7
	v_cvt_pk_bf16_f32 v7, v6, v0
	s_waitcnt lgkmcnt(10)
	v_fma_f32 v58, -v0, v33, v118
	v_fma_f32 v0, v0, v32, v119
	v_fma_f32 v0, v6, v33, v0
	v_fma_f32 v58, v6, v32, v58
	v_cvt_pk_bf16_f32 v6, v58, v0
	ds_write2_b32 v103, v6, v7 offset0:88 offset1:156
	s_waitcnt lgkmcnt(10)
	v_fma_f32 v7, v33, v58, v121
	v_fma_f32 v6, v32, v58, v120
	v_fma_f32 v6, -v33, v0, v6
	v_fma_f32 v0, v32, v0, v7
	v_cvt_pk_bf16_f32 v7, v6, v0
	s_waitcnt lgkmcnt(9)
	v_fma_f32 v58, -v0, v33, v122
	v_fma_f32 v0, v0, v32, v123
	v_fma_f32 v0, v6, v33, v0
	v_fma_f32 v58, v6, v32, v58
	v_cvt_pk_bf16_f32 v6, v58, v0
	ds_write2_b32 v104, v6, v7 offset0:80 offset1:148
	s_waitcnt lgkmcnt(9)
	v_fma_f32 v7, v33, v58, v125
	v_fma_f32 v6, v32, v58, v124
	v_fma_f32 v6, -v33, v0, v6
	v_fma_f32 v0, v32, v0, v7
	v_cvt_pk_bf16_f32 v7, v6, v0
	s_waitcnt lgkmcnt(8)
	v_fma_f32 v58, -v0, v33, v126
	v_fma_f32 v0, v0, v32, v127
	v_fma_f32 v0, v6, v33, v0
	v_fma_f32 v58, v6, v32, v58
	v_cvt_pk_bf16_f32 v6, v58, v0
	ds_write2_b32 v105, v6, v7 offset0:72 offset1:140
	s_waitcnt lgkmcnt(8)
	v_fma_f32 v7, v33, v58, v129
	v_fma_f32 v6, v32, v58, v128
	v_fma_f32 v6, -v33, v0, v6
	v_fma_f32 v7, v32, v0, v7
	v_mul_f32_e32 v0, v33, v7
	v_cvt_pk_bf16_f32 v58, v6, v7
	v_fma_f32 v0, v32, v6, -v0
	v_mul_f32_e32 v6, v33, v6
	v_fmac_f32_e32 v6, v32, v7
	s_waitcnt lgkmcnt(7)
	v_add_f32_e32 v0, v130, v0
	v_add_f32_e32 v6, v131, v6
	v_cvt_pk_bf16_f32 v7, v0, v6
	ds_write2_b32 v106, v7, v58 offset0:64 offset1:132
	s_waitcnt lgkmcnt(0)
	ds_read_b128 v[72:75], v79 offset:11520
	ds_read_b128 v[108:111], v79 offset:11584
	s_waitcnt lgkmcnt(1)
	v_mfma_f32_16x16x32_bf16 v[58:61], v[72:75], v[20:23], v[60:63]
	ds_read_b128 v[72:75], v79 offset:11648
	v_mov_b32_e32 v76, 0
	v_mov_b32_e32 v77, 0
	s_waitcnt lgkmcnt(1)
	v_mfma_f32_16x16x32_bf16 v[58:61], v[108:111], v[28:31], v[58:61]
	ds_read_b128 v[108:111], v79 offset:11712
	s_waitcnt lgkmcnt(1)
	v_mfma_f32_16x16x32_bf16 v[58:61], v[72:75], v[24:27], v[58:61]
	v_mov_b32_e32 v72, 0
	v_mov_b32_e32 v74, 0
	v_mov_b32_e32 v75, 0
	s_waitcnt lgkmcnt(0)
	v_mfma_f32_16x16x32_bf16 v[58:61], v[108:111], v[16:19], v[58:61]
	s_and_saveexec_b64 s[4:5], vcc
	ds_read_b128 v[74:77], v81 offset:768
	s_or_b64 exec, exec, s[4:5]
	s_waitcnt lgkmcnt(0)
	v_mfma_f32_16x16x32_bf16 v[108:111], v[74:77], v[42:45], 0
	v_mul_f32_e32 v7, v33, v6
	v_fma_f32 v7, v32, v0, -v7
	v_mul_f32_e32 v0, v33, v0
	v_mfma_f32_16x16x32_bf16 v[112:115], v[74:77], v[68:71], 0
	s_nop 7
	ds_write2_b32 v80, v108, v112 offset1:16
	ds_write2_b32 v80, v109, v113 offset0:132 offset1:148
	ds_write2_b32 v82, v110, v114 offset0:8 offset1:24
	v_mfma_f32_16x16x32_bf16 v[116:119], v[74:77], v[64:67], 0
	v_fmac_f32_e32 v0, v32, v6
	v_mov_b32_e32 v73, 0
	v_mfma_f32_16x16x32_bf16 v[120:123], v[74:77], v[50:53], 0
	ds_write2_b32 v82, v111, v115 offset0:140 offset1:156
	s_nop 6
	ds_write2_b32 v80, v116, v120 offset0:32 offset1:48
	ds_write2_b32 v80, v117, v121 offset0:164 offset1:180
	v_mfma_f32_16x16x32_bf16 v[124:127], v[74:77], v[54:57], 0
	v_mfma_f32_16x16x32_bf16 v[108:111], v[74:77], v[46:49], 0
	ds_write2_b32 v82, v118, v122 offset0:40 offset1:56
	ds_write2_b32 v82, v119, v123 offset0:172 offset1:188
	s_nop 5
	ds_write2_b32 v80, v124, v108 offset0:64 offset1:80
	ds_write2_b32 v80, v125, v109 offset0:196 offset1:212
	ds_write2_b32 v82, v126, v110 offset0:72 offset1:88
	ds_write2_b32 v82, v127, v111 offset0:204 offset1:220
	v_mfma_f32_16x16x32_bf16 v[112:115], v[74:77], v[38:41], 0
	v_mfma_f32_16x16x32_bf16 v[74:77], v[74:77], v[34:37], 0
	s_nop 7
	ds_write2_b32 v80, v112, v74 offset0:96 offset1:112
	ds_write2_b32 v80, v113, v75 offset0:228 offset1:244
	ds_write2_b32 v82, v114, v76 offset0:104 offset1:120
	ds_write2_b32 v82, v115, v77 offset0:236 offset1:252
	s_waitcnt lgkmcnt(0)
	ds_read2st64_b32 v[62:63], v84 offset0:42 offset1:43
	ds_read2st64_b32 v[74:75], v85 offset0:40 offset1:41
	ds_read2st64_b32 v[76:77], v86 offset0:38 offset1:39
	ds_read2st64_b32 v[108:109], v87 offset0:36 offset1:37
	ds_read2st64_b32 v[110:111], v88 offset0:34 offset1:35
	ds_read2st64_b32 v[112:113], v89 offset0:32 offset1:33
	ds_read2st64_b32 v[114:115], v90 offset0:30 offset1:31
	ds_read2st64_b32 v[116:117], v91 offset0:28 offset1:29
	ds_read2st64_b32 v[118:119], v92 offset0:26 offset1:27
	ds_read2st64_b32 v[120:121], v93 offset0:24 offset1:25
	ds_read2st64_b32 v[122:123], v94 offset0:22 offset1:23
	ds_read2st64_b32 v[124:125], v95 offset0:20 offset1:21
	ds_read2st64_b32 v[126:127], v96 offset0:18 offset1:19
	ds_read2st64_b32 v[128:129], v97 offset0:16 offset1:17
	ds_read2st64_b32 v[130:131], v98 offset0:14 offset1:15
	ds_read2st64_b32 v[132:133], v83 offset0:12 offset1:13
	s_waitcnt lgkmcnt(14)
	v_add_f32_e32 v7, v7, v62
	v_add_f32_e32 v0, v0, v63
	v_cvt_pk_bf16_f32 v6, v7, v0
	v_fma_f32 v62, -v0, v33, v74
	v_fma_f32 v0, v0, v32, v75
	v_fma_f32 v0, v7, v33, v0
	v_fma_f32 v62, v7, v32, v62
	v_cvt_pk_bf16_f32 v7, v62, v0
	ds_write2_b32 v99, v7, v6 offset0:120 offset1:188
	s_waitcnt lgkmcnt(14)
	v_fma_f32 v7, v33, v62, v77
	v_fma_f32 v6, v32, v62, v76
	v_fma_f32 v6, -v33, v0, v6
	v_fma_f32 v0, v32, v0, v7
	v_cvt_pk_bf16_f32 v7, v6, v0
	s_waitcnt lgkmcnt(13)
	v_fma_f32 v62, -v0, v33, v108
	v_fma_f32 v0, v0, v32, v109
	v_fma_f32 v0, v6, v33, v0
	v_fma_f32 v62, v6, v32, v62
	v_cvt_pk_bf16_f32 v6, v62, v0
	ds_write2_b32 v100, v6, v7 offset0:112 offset1:180
	s_waitcnt lgkmcnt(13)
	v_fma_f32 v7, v33, v62, v111
	v_fma_f32 v6, v32, v62, v110
	v_fma_f32 v6, -v33, v0, v6
	v_fma_f32 v0, v32, v0, v7
	v_cvt_pk_bf16_f32 v7, v6, v0
	s_waitcnt lgkmcnt(12)
	v_fma_f32 v62, -v0, v33, v112
	v_fma_f32 v0, v0, v32, v113
	v_fma_f32 v0, v6, v33, v0
	v_fma_f32 v62, v6, v32, v62
	v_cvt_pk_bf16_f32 v6, v62, v0
	ds_write2_b32 v101, v6, v7 offset0:104 offset1:172
	s_waitcnt lgkmcnt(12)
	v_fma_f32 v7, v33, v62, v115
	v_fma_f32 v6, v32, v62, v114
	v_fma_f32 v6, -v33, v0, v6
	v_fma_f32 v0, v32, v0, v7
	v_cvt_pk_bf16_f32 v7, v6, v0
	s_waitcnt lgkmcnt(11)
	v_fma_f32 v62, -v0, v33, v116
	v_fma_f32 v0, v0, v32, v117
	v_fma_f32 v0, v6, v33, v0
	v_fma_f32 v62, v6, v32, v62
	v_cvt_pk_bf16_f32 v6, v62, v0
	ds_write2_b32 v102, v6, v7 offset0:96 offset1:164
	s_waitcnt lgkmcnt(11)
	v_fma_f32 v7, v33, v62, v119
	v_fma_f32 v6, v32, v62, v118
	v_fma_f32 v6, -v33, v0, v6
	v_fma_f32 v0, v32, v0, v7
	v_cvt_pk_bf16_f32 v7, v6, v0
	s_waitcnt lgkmcnt(10)
	v_fma_f32 v62, -v0, v33, v120
	v_fma_f32 v0, v0, v32, v121
	v_fma_f32 v0, v6, v33, v0
	v_fma_f32 v62, v6, v32, v62
	v_cvt_pk_bf16_f32 v6, v62, v0
	ds_write2_b32 v103, v6, v7 offset0:88 offset1:156
	s_waitcnt lgkmcnt(10)
	v_fma_f32 v7, v33, v62, v123
	v_fma_f32 v6, v32, v62, v122
	v_fma_f32 v6, -v33, v0, v6
	v_fma_f32 v0, v32, v0, v7
	v_cvt_pk_bf16_f32 v7, v6, v0
	s_waitcnt lgkmcnt(9)
	v_fma_f32 v62, -v0, v33, v124
	v_fma_f32 v0, v0, v32, v125
	v_fma_f32 v0, v6, v33, v0
	v_fma_f32 v62, v6, v32, v62
	v_cvt_pk_bf16_f32 v6, v62, v0
	ds_write2_b32 v104, v6, v7 offset0:80 offset1:148
	s_waitcnt lgkmcnt(9)
	v_fma_f32 v7, v33, v62, v127
	v_fma_f32 v6, v32, v62, v126
	v_fma_f32 v6, -v33, v0, v6
	v_fma_f32 v0, v32, v0, v7
	v_cvt_pk_bf16_f32 v7, v6, v0
	s_waitcnt lgkmcnt(8)
	v_fma_f32 v62, -v0, v33, v128
	v_fma_f32 v0, v0, v32, v129
	v_fma_f32 v0, v6, v33, v0
	v_fma_f32 v62, v6, v32, v62
	v_cvt_pk_bf16_f32 v6, v62, v0
	ds_write2_b32 v105, v6, v7 offset0:72 offset1:140
	s_waitcnt lgkmcnt(8)
	v_fma_f32 v7, v33, v62, v131
	v_fma_f32 v6, v32, v62, v130
	v_fma_f32 v6, -v33, v0, v6
	v_fma_f32 v7, v32, v0, v7
	v_cvt_pk_bf16_f32 v63, v6, v7
	s_waitcnt lgkmcnt(7)
	v_fma_f32 v0, -v33, v7, v132
	v_fma_f32 v62, v33, v6, v133
	v_fma_f32 v62, v32, v7, v62
	v_fma_f32 v0, v32, v6, v0
	v_cvt_pk_bf16_f32 v6, v0, v62
	ds_write2_b32 v106, v6, v63 offset0:64 offset1:132
	s_waitcnt lgkmcnt(0)
	ds_read_b128 v[74:77], v79 offset:11520
	ds_read_b128 v[108:111], v79 offset:11584
	s_waitcnt lgkmcnt(1)
	v_mfma_f32_16x16x32_bf16 v[6:9], v[74:77], v[20:23], v[8:11]
	ds_read_b128 v[74:77], v79 offset:11648
	s_waitcnt lgkmcnt(1)
	v_mfma_f32_16x16x32_bf16 v[6:9], v[108:111], v[28:31], v[6:9]
	ds_read_b128 v[108:111], v79 offset:11712
	s_waitcnt lgkmcnt(1)
	v_mfma_f32_16x16x32_bf16 v[6:9], v[74:77], v[24:27], v[6:9]
	v_mov_b32_e32 v74, 0
	v_mov_b32_e32 v75, 0
	s_waitcnt lgkmcnt(0)
	v_mfma_f32_16x16x32_bf16 v[6:9], v[108:111], v[16:19], v[6:9]
	s_and_saveexec_b64 s[4:5], vcc
	s_cbranch_execz .LBB0_275
	ds_read_b128 v[72:75], v81
	s_branch .LBB0_275

.LBB0_594:
	s_or_b64 exec, exec, s[0:1]
	v_mul_f32_e32 v0, 0, v3
	v_fma_f32 v159, 0, v2, v0
	v_add_f32_e32 v135, v159, v135
	v_fma_f32 v0, v2, 0, -v0
	v_mul_f32_e32 v159, v2, v135
	v_add_f32_e32 v0, v0, v134
	v_mul_f32_e32 v134, v3, v135
	v_fmac_f32_e32 v159, v3, v0
	v_fma_f32 v0, v2, v0, -v134
	v_add_f32_e32 v0, v132, v0
	v_add_f32_e32 v133, v133, v159
	v_fma_f32 v132, v3, v0, v131
	v_fma_f32 v0, v2, v0, v130
	v_fma_f32 v0, -v3, v133, v0
	v_fma_f32 v131, v2, v133, v132
	v_fma_f32 v130, v3, v0, v127
	v_fma_f32 v0, v2, v0, v126
	v_fma_f32 v0, -v3, v131, v0
	v_fma_f32 v127, v2, v131, v130
	v_fma_f32 v126, v3, v0, v123
	v_fma_f32 v0, v2, v0, v122
	v_fma_f32 v0, -v3, v127, v0
	v_fma_f32 v123, v2, v127, v126
	v_fma_f32 v122, v3, v0, v119
	v_fma_f32 v0, v2, v0, v118
	v_fma_f32 v0, -v3, v123, v0
	v_fma_f32 v119, v2, v123, v122
	v_fma_f32 v118, v3, v0, v117
	v_fma_f32 v0, v2, v0, v116
	v_fma_f32 v0, -v3, v119, v0
	v_fma_f32 v117, v2, v119, v118
	v_fma_f32 v116, v3, v0, v113
	v_fma_f32 v0, v2, v0, v112
	v_fma_f32 v0, -v3, v117, v0
	v_fma_f32 v113, v2, v117, v116
	v_fma_f32 v112, v3, v0, v109
	v_fma_f32 v0, v2, v0, v108
	v_fma_f32 v0, -v3, v113, v0
	v_fma_f32 v109, v2, v113, v112
	v_fma_f32 v108, v3, v0, v103
	v_fma_f32 v0, v2, v0, v102
	v_fma_f32 v0, -v3, v109, v0
	v_fma_f32 v103, v2, v109, v108
	v_fma_f32 v102, v3, v0, v97
	v_fma_f32 v0, v2, v0, v96
	v_fma_f32 v0, -v3, v103, v0
	v_fma_f32 v97, v2, v103, v102
	v_fma_f32 v96, v3, v0, v91
	v_fma_f32 v0, v2, v0, v90
	v_fma_f32 v0, -v3, v97, v0
	v_fma_f32 v91, v2, v97, v96
	v_fma_f32 v90, v3, v0, v87
	v_fma_f32 v0, v2, v0, v86
	v_fma_f32 v0, -v3, v91, v0
	v_fma_f32 v87, v2, v91, v90
	v_fma_f32 v86, v3, v0, v83
	v_fma_f32 v0, v2, v0, v82
	v_fma_f32 v0, -v3, v87, v0
	v_fma_f32 v83, v2, v87, v86
	v_fma_f32 v82, v3, v0, v77
	v_fma_f32 v0, v2, v0, v76
	v_fma_f32 v0, -v3, v83, v0
	v_fma_f32 v77, v2, v83, v82
	v_fma_f32 v76, v3, v0, v71
	v_fma_f32 v0, v2, v0, v70
	v_fma_f32 v0, -v3, v77, v0
	v_fma_f32 v71, v2, v77, v76
	v_mul_f32_e32 v70, v3, v0
	v_fmac_f32_e32 v70, v2, v71
	v_mul_f32_e32 v71, v3, v71
	v_add_f32_e32 v70, v70, v129
	v_fma_f32 v0, v2, v0, -v71
	v_mul_f32_e32 v76, v2, v70
	v_add_f32_e32 v0, v0, v128
	v_mul_f32_e32 v70, v3, v70
	v_fmac_f32_e32 v76, v3, v0
	v_fma_f32 v0, v2, v0, -v70
	v_add_f32_e32 v0, v124, v0
	v_add_f32_e32 v71, v125, v76
	v_fma_f32 v70, v3, v0, v121
	v_fma_f32 v0, v2, v0, v120
	v_fma_f32 v0, -v3, v71, v0
	v_fma_f32 v70, v2, v71, v70
	v_fma_f32 v71, v3, v0, v115
	v_fma_f32 v0, v2, v0, v114
	v_fma_f32 v0, -v3, v70, v0
	v_fma_f32 v71, v2, v70, v71
	v_fma_f32 v70, v3, v0, v111
	v_fma_f32 v0, v2, v0, v110
	v_fma_f32 v0, -v3, v71, v0
	v_fma_f32 v70, v2, v71, v70
	v_fma_f32 v71, v3, v0, v105
	v_fma_f32 v0, v2, v0, v104
	v_fma_f32 v0, -v3, v70, v0
	v_fma_f32 v71, v2, v70, v71
	v_fma_f32 v70, v3, v0, v99
	v_fma_f32 v0, v2, v0, v98
	v_fma_f32 v0, -v3, v71, v0
	v_fma_f32 v70, v2, v71, v70
	v_fma_f32 v71, v3, v0, v93
	v_fma_f32 v0, v2, v0, v92
	v_fma_f32 v0, -v3, v70, v0
	v_fma_f32 v71, v2, v70, v71
	v_fma_f32 v70, v3, v0, v85
	v_fma_f32 v0, v2, v0, v84
	v_fma_f32 v0, -v3, v71, v0
	v_fma_f32 v70, v2, v71, v70
	v_fma_f32 v71, v3, v0, v79
	v_fma_f32 v0, v2, v0, v78
	v_fma_f32 v0, -v3, v70, v0
	v_fma_f32 v71, v2, v70, v71
	v_fma_f32 v70, v3, v0, v73
	v_fma_f32 v0, v2, v0, v72
	v_fma_f32 v0, -v3, v71, v0
	v_fma_f32 v70, v2, v71, v70
	v_fma_f32 v71, v3, v0, v67
	v_fma_f32 v0, v2, v0, v66
	v_fma_f32 v0, -v3, v70, v0
	v_fma_f32 v67, v2, v70, v71
	v_fma_f32 v66, v3, v0, v63
	v_fma_f32 v0, v2, v0, v62
	v_fma_f32 v0, -v3, v67, v0
	v_fma_f32 v63, v2, v67, v66
	v_fma_f32 v62, v3, v0, v59
	v_fma_f32 v0, v2, v0, v58
	v_fma_f32 v0, -v3, v63, v0
	v_fma_f32 v59, v2, v63, v62
	v_fma_f32 v58, v3, v0, v55
	v_fma_f32 v0, v2, v0, v54
	v_fma_f32 v0, -v3, v59, v0
	v_fma_f32 v55, v2, v59, v58
	v_fma_f32 v54, v3, v0, v51
	v_fma_f32 v0, v2, v0, v50
	v_fma_f32 v0, -v3, v55, v0
	v_fma_f32 v51, v2, v55, v54
	v_mul_f32_e32 v50, v3, v0
	v_fmac_f32_e32 v50, v2, v51
	v_mul_f32_e32 v51, v3, v51
	s_waitcnt lgkmcnt(14)
	v_add_f32_e32 v50, v50, v107
	v_fma_f32 v0, v2, v0, -v51
	v_mul_f32_e32 v54, v2, v50
	v_add_f32_e32 v0, v0, v106
	v_mul_f32_e32 v50, v3, v50
	v_fmac_f32_e32 v54, v3, v0
	v_fma_f32 v0, v2, v0, -v50
	v_add_f32_e32 v0, v100, v0
	v_add_f32_e32 v51, v101, v54
	s_waitcnt lgkmcnt(13)
	v_fma_f32 v50, v3, v0, v95
	v_fma_f32 v0, v2, v0, v94
	v_fma_f32 v0, -v3, v51, v0
	v_fma_f32 v50, v2, v51, v50
	s_waitcnt lgkmcnt(12)
	v_fma_f32 v51, v3, v0, v89
	v_fma_f32 v0, v2, v0, v88
	v_fma_f32 v0, -v3, v50, v0
	v_fma_f32 v51, v2, v50, v51
	s_waitcnt lgkmcnt(11)
	v_fma_f32 v50, v3, v0, v81
	v_fma_f32 v0, v2, v0, v80
	v_fma_f32 v0, -v3, v51, v0
	v_fma_f32 v50, v2, v51, v50
	s_waitcnt lgkmcnt(10)
	v_fma_f32 v51, v3, v0, v75
	v_fma_f32 v0, v2, v0, v74
	v_fma_f32 v0, -v3, v50, v0
	v_fma_f32 v51, v2, v50, v51
	s_waitcnt lgkmcnt(9)
	v_fma_f32 v50, v3, v0, v69
	v_fma_f32 v0, v2, v0, v68
	v_fma_f32 v0, -v3, v51, v0
	v_fma_f32 v50, v2, v51, v50
	s_waitcnt lgkmcnt(8)
	v_fma_f32 v51, v3, v0, v65
	v_fma_f32 v0, v2, v0, v64
	v_fma_f32 v0, -v3, v50, v0
	v_fma_f32 v51, v2, v50, v51
	s_waitcnt lgkmcnt(7)
	v_fma_f32 v50, v3, v0, v61
	v_fma_f32 v0, v2, v0, v60
	v_fma_f32 v0, -v3, v51, v0
	v_fma_f32 v50, v2, v51, v50
	s_waitcnt lgkmcnt(6)
	v_fma_f32 v51, v3, v0, v57
	v_fma_f32 v0, v2, v0, v56
	v_fma_f32 v0, -v3, v50, v0
	v_fma_f32 v51, v2, v50, v51
	s_waitcnt lgkmcnt(5)
	v_fma_f32 v50, v3, v0, v53
	v_fma_f32 v0, v2, v0, v52
	v_fma_f32 v0, -v3, v51, v0
	v_fma_f32 v50, v2, v51, v50
	s_waitcnt lgkmcnt(4)
	v_fma_f32 v51, v3, v0, v49
	v_fma_f32 v0, v2, v0, v48
	v_fma_f32 v0, -v3, v50, v0
	v_fma_f32 v49, v2, v50, v51
	s_waitcnt lgkmcnt(3)
	v_fma_f32 v48, v3, v0, v47
	v_fma_f32 v0, v2, v0, v46
	v_fma_f32 v0, -v3, v49, v0
	v_fma_f32 v47, v2, v49, v48
	s_waitcnt lgkmcnt(2)
	v_fma_f32 v46, v3, v0, v45
	v_fma_f32 v0, v2, v0, v44
	v_fma_f32 v0, -v3, v47, v0
	v_fma_f32 v45, v2, v47, v46
	s_waitcnt lgkmcnt(1)
	v_fma_f32 v44, v3, v0, v43
	v_fma_f32 v0, v2, v0, v42
	v_fma_f32 v0, -v3, v45, v0
	v_fma_f32 v43, v2, v45, v44
	s_waitcnt lgkmcnt(0)
	v_mfma_f32_16x16x32_bf16 v[32:35], v[36:39], v[32:35], 0
	v_mfma_f32_16x16x32_bf16 v[28:31], v[36:39], v[28:31], 0
	v_fma_f32 v42, v3, v0, v41
	v_fma_f32 v0, v2, v0, v40
	v_fma_f32 v0, -v3, v43, v0
	v_fma_f32 v41, v2, v43, v42
	s_nop 5
	ds_write2_b32 v137, v32, v28 offset1:16
	ds_write2_b32 v137, v33, v29 offset0:132 offset1:148
	ds_write2_b32 v138, v34, v30 offset0:8 offset1:24
	v_mfma_f32_16x16x32_bf16 v[24:27], v[36:39], v[24:27], 0
	s_or_b32 s0, s11, 1
	s_mul_hi_i32 s1, s0, 0x44
	s_mulk_i32 s0, 0x44
	v_mfma_f32_16x16x32_bf16 v[16:19], v[36:39], v[16:19], 0
	ds_write2_b32 v138, v35, v31 offset0:140 offset1:156
	s_nop 6
	ds_write2_b32 v137, v24, v16 offset0:32 offset1:48
	ds_write2_b32 v137, v25, v17 offset0:164 offset1:180
	v_mfma_f32_16x16x32_bf16 v[20:23], v[36:39], v[20:23], 0
	s_add_u32 s0, s0, s9
	s_addc_u32 s1, s1, s10
	s_lshl_b64 s[0:1], s[0:1], 10
	v_mfma_f32_16x16x32_bf16 v[12:15], v[36:39], v[12:15], 0
	ds_write2_b32 v138, v26, v18 offset0:40 offset1:56
	ds_write2_b32 v138, v27, v19 offset0:172 offset1:188
	s_nop 5
	ds_write2_b32 v137, v20, v12 offset0:64 offset1:80
	ds_write2_b32 v137, v21, v13 offset0:196 offset1:212
	ds_write2_b32 v138, v22, v14 offset0:72 offset1:88
	ds_write2_b32 v138, v23, v15 offset0:204 offset1:220
	v_mfma_f32_16x16x32_bf16 v[8:11], v[36:39], v[8:11], 0
	s_add_u32 s0, s0, s4
	s_addc_u32 s1, s1, s5
	s_add_i32 s6, s6, s54
	v_mfma_f32_16x16x32_bf16 v[4:7], v[36:39], v[4:7], 0
	v_mul_f32_e32 v36, v3, v41
	s_nop 6
	ds_write2_b32 v137, v8, v4 offset0:96 offset1:112
	ds_write2_b32 v137, v9, v5 offset0:228 offset1:244
	ds_write2_b32 v138, v10, v6 offset0:104 offset1:120
	ds_write2_b32 v138, v11, v7 offset0:236 offset1:252
	v_fma_f32 v36, v2, v0, -v36
	v_mul_f32_e32 v0, v3, v0
	s_waitcnt lgkmcnt(0)
	v_fmac_f32_e32 v0, v2, v41
	ds_read2st64_b32 v[4:5], v140 offset0:42 offset1:43
	ds_read2st64_b32 v[6:7], v141 offset0:40 offset1:41
	ds_read2st64_b32 v[8:9], v146 offset0:38 offset1:39
	ds_read2st64_b32 v[10:11], v147 offset0:36 offset1:37
	ds_read2st64_b32 v[12:13], v148 offset0:34 offset1:35
	ds_read2st64_b32 v[14:15], v149 offset0:32 offset1:33
	ds_read2st64_b32 v[16:17], v150 offset0:30 offset1:31
	ds_read2st64_b32 v[18:19], v151 offset0:28 offset1:29
	ds_read2st64_b32 v[20:21], v152 offset0:26 offset1:27
	ds_read2st64_b32 v[22:23], v153 offset0:24 offset1:25
	ds_read2st64_b32 v[24:25], v154 offset0:22 offset1:23
	ds_read2st64_b32 v[26:27], v155 offset0:20 offset1:21
	ds_read2st64_b32 v[28:29], v156 offset0:18 offset1:19
	ds_read2st64_b32 v[30:31], v157 offset0:16 offset1:17
	ds_read2st64_b32 v[32:33], v158 offset0:14 offset1:15
	ds_read2st64_b32 v[34:35], v139 offset0:12 offset1:13
	s_waitcnt lgkmcnt(14)
	v_add_f32_e32 v0, v0, v5
	v_add_f32_e32 v4, v36, v4
	v_fma_f32 v5, -v0, v3, v6
	v_fma_f32 v0, v0, v2, v7
	v_fma_f32 v0, v4, v3, v0
	v_fma_f32 v5, v4, v2, v5
	s_waitcnt lgkmcnt(13)
	v_fma_f32 v4, -v0, v3, v8
	v_fma_f32 v0, v0, v2, v9
	v_fma_f32 v0, v5, v3, v0
	v_fma_f32 v4, v5, v2, v4
	s_waitcnt lgkmcnt(12)
	v_fma_f32 v5, -v0, v3, v10
	v_fma_f32 v0, v0, v2, v11
	v_fma_f32 v0, v4, v3, v0
	v_fma_f32 v5, v4, v2, v5
	s_waitcnt lgkmcnt(11)
	v_fma_f32 v4, -v0, v3, v12
	v_fma_f32 v0, v0, v2, v13
	v_fma_f32 v0, v5, v3, v0
	v_fma_f32 v4, v5, v2, v4
	s_waitcnt lgkmcnt(10)
	v_fma_f32 v5, -v0, v3, v14
	v_fma_f32 v0, v0, v2, v15
	v_fma_f32 v0, v4, v3, v0
	v_fma_f32 v5, v4, v2, v5
	s_waitcnt lgkmcnt(9)
	v_fma_f32 v4, -v0, v3, v16
	v_fma_f32 v0, v0, v2, v17
	v_fma_f32 v0, v5, v3, v0
	v_fma_f32 v4, v5, v2, v4
	s_waitcnt lgkmcnt(8)
	v_fma_f32 v5, -v0, v3, v18
	v_fma_f32 v0, v0, v2, v19
	v_fma_f32 v0, v4, v3, v0
	v_fma_f32 v5, v4, v2, v5
	s_waitcnt lgkmcnt(7)
	v_fma_f32 v4, -v0, v3, v20
	v_fma_f32 v0, v0, v2, v21
	v_fma_f32 v0, v5, v3, v0
	v_fma_f32 v4, v5, v2, v4
	s_waitcnt lgkmcnt(6)
	v_fma_f32 v5, -v0, v3, v22
	v_fma_f32 v0, v0, v2, v23
	v_fma_f32 v0, v4, v3, v0
	v_fma_f32 v5, v4, v2, v5
	s_waitcnt lgkmcnt(5)
	v_fma_f32 v4, -v0, v3, v24
	v_fma_f32 v0, v0, v2, v25
	v_fma_f32 v0, v5, v3, v0
	v_fma_f32 v4, v5, v2, v4
	s_waitcnt lgkmcnt(4)
	v_fma_f32 v5, -v0, v3, v26
	v_fma_f32 v0, v0, v2, v27
	v_fma_f32 v0, v4, v3, v0
	v_fma_f32 v5, v4, v2, v5
	s_waitcnt lgkmcnt(3)
	v_fma_f32 v4, -v0, v3, v28
	v_fma_f32 v0, v0, v2, v29
	v_fma_f32 v0, v5, v3, v0
	v_fma_f32 v4, v5, v2, v4
	s_waitcnt lgkmcnt(2)
	v_fma_f32 v5, -v0, v3, v30
	v_fma_f32 v0, v0, v2, v31
	v_fma_f32 v0, v4, v3, v0
	v_fma_f32 v5, v4, v2, v5
	s_waitcnt lgkmcnt(1)
	v_fma_f32 v4, v3, v5, v33
	v_fma_f32 v6, v2, v5, v32
	v_fma_f32 v6, -v3, v0, v6
	v_fma_f32 v0, v2, v0, v4
	v_mul_f32_e32 v4, v3, v0
	v_mul_f32_e32 v3, v3, v6
	v_fmac_f32_e32 v3, v2, v0
	s_waitcnt lgkmcnt(0)
	v_mov_b32_e32 v0, s59
	v_fma_f32 v4, v2, v6, -v4
	s_waitcnt lgkmcnt(0)
	v_add_f32_e32 v5, v35, v3
	ds_read_b64 v[2:3], v0
	v_or_b32_e32 v6, s0, v136
	v_mov_b32_e32 v7, s1
	v_add_f32_e32 v4, v34, v4
	s_add_i32 s8, s8, s60
	s_waitcnt lgkmcnt(0)
	v_readfirstlane_b32 s0, v3
	v_readfirstlane_b32 s1, v2
	s_cmpk_lt_i32 s6, 0x440
	v_mov_b32_e32 v3, s0
	v_mov_b32_e32 v2, s1
	v_lshl_add_u64 v[2:3], v[6:7], 3, v[2:3]
	v_add_co_u32_e32 v2, vcc, 0xc00000, v2
	s_nop 1
	v_addc_co_u32_e32 v3, vcc, 0, v3, vcc
	global_store_dwordx2 v[2:3], v[4:5], off
	s_waitcnt lgkmcnt(0)
	s_cbranch_scc0 .LBB0_615

.LBB0_599:
	s_and_b32 s0, s8, 8
	v_mov_b64_e32 v[4:5], s[4:5]
	s_add_i32 s0, s0, s7
	v_mad_i64_i32 v[2:3], s[4:5], v2, s94, v[4:5]
	s_lshl_b32 s4, s0, 4
	s_ashr_i32 s5, s4, 31
	v_lshl_add_u64 v[2:3], s[4:5], 1, v[2:3]
	s_mov_b64 s[4:5], 0xe001000
	v_add_co_u32_e32 v6, vcc, 0xe001000, v2
	v_lshl_add_u64 v[4:5], v[2:3], 0, s[4:5]
	s_nop 0
	v_addc_co_u32_e32 v7, vcc, 0, v3, vcc
	global_load_dwordx4 v[2:5], v[4:5], off offset:16
	s_nop 0
	global_load_dwordx4 v[6:9], v[6:7], off
	s_lshr_b32 s1, s11, 6
	s_mulk_i32 s1, 0x3e00
	s_add_i32 s1, s1, 0
	v_mad_u32_u24 v0, v0, 48, s1
	s_waitcnt vmcnt(0)
	v_mov_b32_e32 v37, v204
	v_mov_b32_e32 v10, s59
	s_add_i32 s4, s0, s21
	s_ashr_i32 s5, s4, 31
	s_lshl_b64 s[22:23], s[4:5], 13
	v_mov_b32_e32 v11, v1
	s_mov_b32 s11, 0x200000
	v_mov_b32_e32 v36, 0
	v_mov_b32_e32 v38, 0
	v_mov_b32_e32 v39, 0
	v_mov_b32_e32 v40, 0
	v_mov_b32_e32 v41, 0
	s_waitcnt lgkmcnt(0)
	ds_write_b128 v0, v[2:5] offset:16
	ds_write_b128 v0, v[6:9]
	s_waitcnt lgkmcnt(0)
	ds_read_b64 v[2:3], v10
	v_readfirstlane_b32 s1, v37
	v_and_b32_e32 v136, 63, v37
	s_lshr_b32 s1, s1, 6
	v_lshl_or_b32 v4, s4, 6, v136
	s_mulk_i32 s1, 0x3e00
	v_ashrrev_i32_e32 v5, 31, v4
	s_add_i32 s1, s1, 0
	s_waitcnt lgkmcnt(0)
	v_readfirstlane_b32 s5, v3
	v_readfirstlane_b32 s4, v2
	v_and_b32_e32 v42, 15, v37
	v_and_b32_e32 v0, 48, v37
	v_lshl_add_u64 v[2:3], v[4:5], 4, s[4:5]
	s_add_u32 s4, s4, s22
	s_addc_u32 s5, s5, s23
	v_lshlrev_b32_e32 v10, 6, v42
	v_lshl_add_u64 v[4:5], s[4:5], 0, v[0:1]
	v_add_co_u32_e32 v2, vcc, s11, v2
	v_lshl_add_u64 v[6:7], v[4:5], 0, v[10:11]
	s_mov_b64 s[4:5], 0x240000
	v_addc_co_u32_e32 v3, vcc, 0, v3, vcc
	v_lshl_add_u64 v[8:9], v[6:7], 0, s[4:5]
	s_mov_b32 s4, 0x240000
	v_add_co_u32_e32 v10, vcc, s4, v6
	global_load_dwordx4 v[2:5], v[2:3], off
	s_nop 0
	global_load_dwordx4 v[28:31], v[8:9], off offset:1024
	global_load_dwordx4 v[20:23], v[8:9], off offset:2048
	global_load_dwordx4 v[12:15], v[8:9], off offset:3072
	s_mov_b64 s[36:37], vcc
	s_waitcnt vmcnt(0) lgkmcnt(0)
	v_add_co_u32_e32 v4, vcc, 0x241000, v6
	v_addc_co_u32_e64 v11, s[36:37], 0, v7, s[36:37]
	s_nop 0
	v_addc_co_u32_e32 v5, vcc, 0, v7, vcc
	global_load_dwordx4 v[32:35], v[10:11], off
	global_load_dwordx4 v[24:27], v[4:5], off
	global_load_dwordx4 v[16:19], v[4:5], off offset:1024
	s_nop 0
	global_load_dwordx4 v[8:11], v[4:5], off offset:2048
	s_nop 0
	global_load_dwordx4 v[4:7], v[4:5], off offset:3072
	v_add_u32_e32 v0, s1, v0
	v_cmp_gt_u32_e32 vcc, 32, v136
	v_mad_u32_u24 v158, v42, 48, v0
	s_and_saveexec_b64 s[4:5], vcc
	ds_read_b128 v[38:41], v158
	s_or_b64 exec, exec, s[4:5]
	s_waitcnt vmcnt(0) lgkmcnt(0)
	v_mfma_f32_16x16x32_bf16 v[44:47], v[38:41], v[32:35], 0
	v_bfe_u32 v0, v37, 4, 2
	v_lshlrev_b32_e32 v37, 2, v42
	v_mul_u32_u24_e32 v0, 0x840, v0
	v_mfma_f32_16x16x32_bf16 v[48:51], v[38:41], v[28:31], 0
	v_add3_u32 v37, s1, v37, v0
	v_add_u32_e32 v0, 0xc00, v37
	v_add_u32_e32 v137, 0x1000, v37
	v_mfma_f32_16x16x32_bf16 v[52:55], v[38:41], v[20:23], 0
	v_lshl_add_u32 v138, v136, 2, s1
	s_nop 2
	ds_write2_b32 v0, v44, v48 offset1:16
	ds_write2_b32 v0, v45, v49 offset0:132 offset1:148
	v_mfma_f32_16x16x32_bf16 v[56:59], v[38:41], v[12:15], 0
	ds_write2_b32 v137, v46, v50 offset0:8 offset1:24
	ds_write2_b32 v137, v47, v51 offset0:140 offset1:156
	s_nop 5
	ds_write2_b32 v0, v52, v56 offset0:32 offset1:48
	ds_write2_b32 v0, v53, v57 offset0:164 offset1:180
	v_mfma_f32_16x16x32_bf16 v[42:45], v[38:41], v[24:27], 0
	v_add_u32_e32 v139, 16, v138
	v_add_u32_e32 v140, 32, v138
	v_add_u32_e32 v141, 48, v138
	v_mfma_f32_16x16x32_bf16 v[46:49], v[38:41], v[16:19], 0
	ds_write2_b32 v137, v54, v58 offset0:40 offset1:56
	ds_write2_b32 v137, v55, v59 offset0:172 offset1:188
	s_nop 5
	ds_write2_b32 v0, v42, v46 offset0:64 offset1:80
	ds_write2_b32 v0, v43, v47 offset0:196 offset1:212
	ds_write2_b32 v137, v44, v48 offset0:72 offset1:88
	ds_write2_b32 v137, v45, v49 offset0:204 offset1:220
	v_mfma_f32_16x16x32_bf16 v[50:53], v[38:41], v[8:11], 0
	v_add_u32_e32 v146, 64, v138
	v_add_u32_e32 v147, 0x50, v138
	v_add_u32_e32 v148, 0x60, v138
	v_mfma_f32_16x16x32_bf16 v[38:41], v[38:41], v[4:7], 0
	s_nop 7
	ds_write2_b32 v0, v50, v38 offset0:96 offset1:112
	ds_write2_b32 v0, v51, v39 offset0:228 offset1:244
	ds_write2_b32 v137, v52, v40 offset0:104 offset1:120
	ds_write2_b32 v137, v53, v41 offset0:236 offset1:252
	s_waitcnt lgkmcnt(0)
	v_add_u32_e32 v149, 0x70, v138
	v_add_u32_e32 v150, 0x80, v138
	v_add_u32_e32 v151, 0x90, v138
	v_add_u32_e32 v152, 0xa0, v138
	v_add_u32_e32 v153, 0xb0, v138
	v_add_u32_e32 v154, 0xc0, v138
	v_add_u32_e32 v155, 0xd0, v138
	v_add_u32_e32 v156, 0xe0, v138
	v_add_u32_e32 v157, 0xf0, v138
	ds_read2st64_b32 v[134:135], v138 offset0:12 offset1:13
	ds_read2st64_b32 v[132:133], v139 offset0:14 offset1:15
	ds_read2st64_b32 v[130:131], v140 offset0:16 offset1:17
	ds_read2st64_b32 v[128:129], v141 offset0:18 offset1:19
	ds_read2st64_b32 v[124:125], v146 offset0:20 offset1:21
	ds_read2st64_b32 v[120:121], v147 offset0:22 offset1:23
	ds_read2st64_b32 v[116:117], v148 offset0:24 offset1:25
	ds_read2st64_b32 v[112:113], v149 offset0:26 offset1:27
	ds_read2st64_b32 v[108:109], v150 offset0:28 offset1:29
	ds_read2st64_b32 v[102:103], v151 offset0:30 offset1:31
	ds_read2st64_b32 v[98:99], v152 offset0:32 offset1:33
	ds_read2st64_b32 v[94:95], v153 offset0:34 offset1:35
	ds_read2st64_b32 v[88:89], v154 offset0:36 offset1:37
	ds_read2st64_b32 v[82:83], v155 offset0:38 offset1:39
	ds_read2st64_b32 v[76:77], v156 offset0:40 offset1:41
	ds_read2st64_b32 v[70:71], v157 offset0:42 offset1:43
	s_waitcnt lgkmcnt(0)
	v_mov_b32_e32 v37, 0
	v_mov_b32_e32 v38, 0
	v_mov_b32_e32 v39, 0
	s_and_saveexec_b64 s[4:5], vcc
	ds_read_b128 v[36:39], v158 offset:768
	s_or_b64 exec, exec, s[4:5]
	s_waitcnt lgkmcnt(0)
	v_mfma_f32_16x16x32_bf16 v[40:43], v[36:39], v[32:35], 0
	v_mfma_f32_16x16x32_bf16 v[44:47], v[36:39], v[28:31], 0
	s_nop 7
	ds_write2_b32 v0, v40, v44 offset1:16
	ds_write2_b32 v0, v41, v45 offset0:132 offset1:148
	ds_write2_b32 v137, v42, v46 offset0:8 offset1:24
	v_mfma_f32_16x16x32_bf16 v[48:51], v[36:39], v[20:23], 0
	v_mfma_f32_16x16x32_bf16 v[52:55], v[36:39], v[12:15], 0
	ds_write2_b32 v137, v43, v47 offset0:140 offset1:156
	s_nop 6
	ds_write2_b32 v0, v48, v52 offset0:32 offset1:48
	ds_write2_b32 v0, v49, v53 offset0:164 offset1:180
	v_mfma_f32_16x16x32_bf16 v[56:59], v[36:39], v[24:27], 0
	v_mfma_f32_16x16x32_bf16 v[40:43], v[36:39], v[16:19], 0
	ds_write2_b32 v137, v50, v54 offset0:40 offset1:56
	ds_write2_b32 v137, v51, v55 offset0:172 offset1:188
	s_nop 5
	ds_write2_b32 v0, v56, v40 offset0:64 offset1:80
	ds_write2_b32 v0, v57, v41 offset0:196 offset1:212
	ds_write2_b32 v137, v58, v42 offset0:72 offset1:88
	ds_write2_b32 v137, v59, v43 offset0:204 offset1:220
	v_mfma_f32_16x16x32_bf16 v[44:47], v[36:39], v[8:11], 0
	v_mov_b32_e32 v40, 0
	v_mov_b32_e32 v41, 0
	v_mfma_f32_16x16x32_bf16 v[36:39], v[36:39], v[4:7], 0
	s_nop 7
	ds_write2_b32 v0, v44, v36 offset0:96 offset1:112
	ds_write2_b32 v0, v45, v37 offset0:228 offset1:244
	ds_write2_b32 v137, v46, v38 offset0:104 offset1:120
	ds_write2_b32 v137, v47, v39 offset0:236 offset1:252
	s_waitcnt lgkmcnt(0)
	ds_read2st64_b32 v[126:127], v138 offset0:12 offset1:13
	ds_read2st64_b32 v[122:123], v139 offset0:14 offset1:15
	ds_read2st64_b32 v[118:119], v140 offset0:16 offset1:17
	ds_read2st64_b32 v[114:115], v141 offset0:18 offset1:19
	ds_read2st64_b32 v[110:111], v146 offset0:20 offset1:21
	ds_read2st64_b32 v[104:105], v147 offset0:22 offset1:23
	ds_read2st64_b32 v[96:97], v148 offset0:24 offset1:25
	ds_read2st64_b32 v[90:91], v149 offset0:26 offset1:27
	ds_read2st64_b32 v[84:85], v150 offset0:28 offset1:29
	ds_read2st64_b32 v[78:79], v151 offset0:30 offset1:31
	ds_read2st64_b32 v[72:73], v152 offset0:32 offset1:33
	ds_read2st64_b32 v[66:67], v153 offset0:34 offset1:35
	ds_read2st64_b32 v[62:63], v154 offset0:36 offset1:37
	ds_read2st64_b32 v[58:59], v155 offset0:38 offset1:39
	ds_read2st64_b32 v[54:55], v156 offset0:40 offset1:41
	ds_read2st64_b32 v[50:51], v157 offset0:42 offset1:43
	s_waitcnt lgkmcnt(0)
	v_mov_b32_e32 v36, 0
	v_mov_b32_e32 v38, 0
	v_mov_b32_e32 v39, 0
	s_and_saveexec_b64 s[4:5], vcc
	ds_read_b128 v[38:41], v158 offset:1536
	s_or_b64 exec, exec, s[4:5]
	s_waitcnt lgkmcnt(0)
	v_mfma_f32_16x16x32_bf16 v[42:45], v[38:41], v[32:35], 0
	v_mov_b32_e32 v37, 0
	v_mfma_f32_16x16x32_bf16 v[46:49], v[38:41], v[28:31], 0
	s_nop 7
	ds_write2_b32 v0, v42, v46 offset1:16
	ds_write2_b32 v0, v43, v47 offset0:132 offset1:148
	ds_write2_b32 v137, v44, v48 offset0:8 offset1:24
	v_mfma_f32_16x16x32_bf16 v[160:163], v[38:41], v[20:23], 0
	v_mfma_f32_16x16x32_bf16 v[164:167], v[38:41], v[12:15], 0
	ds_write2_b32 v137, v45, v49 offset0:140 offset1:156
	s_nop 6
	ds_write2_b32 v0, v160, v164 offset0:32 offset1:48
	ds_write2_b32 v0, v161, v165 offset0:164 offset1:180
	v_mfma_f32_16x16x32_bf16 v[168:171], v[38:41], v[24:27], 0
	v_mfma_f32_16x16x32_bf16 v[42:45], v[38:41], v[16:19], 0
	ds_write2_b32 v137, v162, v166 offset0:40 offset1:56
	ds_write2_b32 v137, v163, v167 offset0:172 offset1:188
	s_nop 5
	ds_write2_b32 v0, v168, v42 offset0:64 offset1:80
	ds_write2_b32 v0, v169, v43 offset0:196 offset1:212
	ds_write2_b32 v137, v170, v44 offset0:72 offset1:88
	ds_write2_b32 v137, v171, v45 offset0:204 offset1:220
	v_mfma_f32_16x16x32_bf16 v[46:49], v[38:41], v[8:11], 0
	v_mfma_f32_16x16x32_bf16 v[38:41], v[38:41], v[4:7], 0
	s_nop 7
	ds_write2_b32 v0, v46, v38 offset0:96 offset1:112
	ds_write2_b32 v0, v47, v39 offset0:228 offset1:244
	ds_write2_b32 v137, v48, v40 offset0:104 offset1:120
	ds_write2_b32 v137, v49, v41 offset0:236 offset1:252
	s_waitcnt lgkmcnt(0)
	ds_read2st64_b32 v[106:107], v138 offset0:12 offset1:13
	ds_read2st64_b32 v[100:101], v139 offset0:14 offset1:15
	ds_read2st64_b32 v[92:93], v140 offset0:16 offset1:17
	ds_read2st64_b32 v[86:87], v141 offset0:18 offset1:19
	ds_read2st64_b32 v[80:81], v146 offset0:20 offset1:21
	ds_read2st64_b32 v[74:75], v147 offset0:22 offset1:23
	ds_read2st64_b32 v[68:69], v148 offset0:24 offset1:25
	ds_read2st64_b32 v[64:65], v149 offset0:26 offset1:27
	ds_read2st64_b32 v[60:61], v150 offset0:28 offset1:29
	ds_read2st64_b32 v[56:57], v151 offset0:30 offset1:31
	ds_read2st64_b32 v[52:53], v152 offset0:32 offset1:33
	ds_read2st64_b32 v[48:49], v153 offset0:34 offset1:35
	ds_read2st64_b32 v[46:47], v154 offset0:36 offset1:37
	ds_read2st64_b32 v[44:45], v155 offset0:38 offset1:39
	ds_read2st64_b32 v[42:43], v156 offset0:40 offset1:41
	ds_read2st64_b32 v[40:41], v157 offset0:42 offset1:43
	s_waitcnt lgkmcnt(0)
	v_mov_b32_e32 v38, 0
	v_mov_b32_e32 v39, 0
	s_and_saveexec_b64 s[4:5], vcc
	ds_read_b128 v[36:39], v158 offset:2304
	s_or_b64 exec, exec, s[4:5]
	v_mul_f32_e32 v158, 0, v3
	v_fma_f32 v159, 0, v2, v158
	v_add_f32_e32 v135, v159, v135
	v_fma_f32 v158, v2, 0, -v158
	v_mul_f32_e32 v159, v2, v135
	v_add_f32_e32 v134, v158, v134
	v_mul_f32_e32 v135, v3, v135
	v_fmac_f32_e32 v159, v3, v134
	v_fma_f32 v134, v2, v134, -v135
	v_add_f32_e32 v132, v132, v134
	v_add_f32_e32 v133, v133, v159
	v_fma_f32 v134, v3, v132, v131
	v_fma_f32 v130, v2, v132, v130
	v_fma_f32 v130, -v3, v133, v130
	v_fma_f32 v131, v2, v133, v134
	v_fma_f32 v132, v3, v130, v129
	v_fma_f32 v128, v2, v130, v128
	v_fma_f32 v128, -v3, v131, v128
	v_fma_f32 v129, v2, v131, v132
	v_fma_f32 v130, v3, v128, v125
	v_fma_f32 v124, v2, v128, v124
	v_fma_f32 v124, -v3, v129, v124
	v_fma_f32 v125, v2, v129, v130
	v_fma_f32 v128, v3, v124, v121
	v_fma_f32 v120, v2, v124, v120
	v_fma_f32 v120, -v3, v125, v120
	v_fma_f32 v121, v2, v125, v128
	v_fma_f32 v124, v3, v120, v117
	v_fma_f32 v116, v2, v120, v116
	v_fma_f32 v116, -v3, v121, v116
	v_fma_f32 v117, v2, v121, v124
	v_fma_f32 v120, v3, v116, v113
	v_fma_f32 v112, v2, v116, v112
	v_fma_f32 v112, -v3, v117, v112
	v_fma_f32 v113, v2, v117, v120
	v_fma_f32 v116, v3, v112, v109
	v_fma_f32 v108, v2, v112, v108
	v_fma_f32 v108, -v3, v113, v108
	v_fma_f32 v109, v2, v113, v116
	v_fma_f32 v112, v3, v108, v103
	v_fma_f32 v102, v2, v108, v102
	v_fma_f32 v102, -v3, v109, v102
	v_fma_f32 v103, v2, v109, v112
	v_fma_f32 v108, v3, v102, v99
	v_fma_f32 v98, v2, v102, v98
	v_fma_f32 v98, -v3, v103, v98
	v_fma_f32 v99, v2, v103, v108
	v_fma_f32 v102, v3, v98, v95
	v_fma_f32 v94, v2, v98, v94
	v_fma_f32 v94, -v3, v99, v94
	v_fma_f32 v95, v2, v99, v102
	v_fma_f32 v98, v3, v94, v89
	v_fma_f32 v88, v2, v94, v88
	v_fma_f32 v88, -v3, v95, v88
	v_fma_f32 v89, v2, v95, v98
	v_fma_f32 v94, v3, v88, v83
	v_fma_f32 v82, v2, v88, v82
	v_fma_f32 v82, -v3, v89, v82
	v_fma_f32 v83, v2, v89, v94
	v_fma_f32 v88, v3, v82, v77
	v_fma_f32 v76, v2, v82, v76
	v_fma_f32 v76, -v3, v83, v76
	v_fma_f32 v77, v2, v83, v88
	v_fma_f32 v82, v3, v76, v71
	v_fma_f32 v70, v2, v76, v70
	v_fma_f32 v70, -v3, v77, v70
	v_fma_f32 v71, v2, v77, v82
	v_mul_f32_e32 v76, v3, v70
	v_fmac_f32_e32 v76, v2, v71
	v_mul_f32_e32 v71, v3, v71
	v_add_f32_e32 v76, v76, v127
	v_fma_f32 v70, v2, v70, -v71
	v_mul_f32_e32 v77, v2, v76
	v_add_f32_e32 v70, v70, v126
	v_mul_f32_e32 v76, v3, v76
	v_fmac_f32_e32 v77, v3, v70
	v_fma_f32 v70, v2, v70, -v76
	v_add_f32_e32 v70, v122, v70
	v_add_f32_e32 v71, v123, v77
	v_fma_f32 v76, v3, v70, v119
	v_fma_f32 v70, v2, v70, v118
	v_fma_f32 v70, -v3, v71, v70
	v_fma_f32 v76, v2, v71, v76
	v_fma_f32 v71, v3, v70, v115
	v_fma_f32 v70, v2, v70, v114
	v_fma_f32 v70, -v3, v76, v70
	v_fma_f32 v71, v2, v76, v71
	v_fma_f32 v76, v3, v70, v111
	v_fma_f32 v70, v2, v70, v110
	v_fma_f32 v70, -v3, v71, v70
	v_fma_f32 v76, v2, v71, v76
	v_fma_f32 v71, v3, v70, v105
	v_fma_f32 v70, v2, v70, v104
	v_fma_f32 v70, -v3, v76, v70
	v_fma_f32 v71, v2, v76, v71
	v_fma_f32 v76, v3, v70, v97
	v_fma_f32 v70, v2, v70, v96
	v_fma_f32 v70, -v3, v71, v70
	v_fma_f32 v76, v2, v71, v76
	v_fma_f32 v71, v3, v70, v91
	v_fma_f32 v70, v2, v70, v90
	v_fma_f32 v70, -v3, v76, v70
	v_fma_f32 v71, v2, v76, v71
	v_fma_f32 v76, v3, v70, v85
	v_fma_f32 v70, v2, v70, v84
	v_fma_f32 v70, -v3, v71, v70
	v_fma_f32 v76, v2, v71, v76
	v_fma_f32 v71, v3, v70, v79
	v_fma_f32 v70, v2, v70, v78
	v_fma_f32 v70, -v3, v76, v70
	v_fma_f32 v71, v2, v76, v71
	v_fma_f32 v76, v3, v70, v73
	v_fma_f32 v70, v2, v70, v72
	v_fma_f32 v70, -v3, v71, v70
	v_fma_f32 v73, v2, v71, v76
	v_fma_f32 v71, v3, v70, v67
	v_fma_f32 v66, v2, v70, v66
	v_fma_f32 v66, -v3, v73, v66
	v_fma_f32 v67, v2, v73, v71
	v_fma_f32 v70, v3, v66, v63
	v_fma_f32 v62, v2, v66, v62
	v_fma_f32 v62, -v3, v67, v62
	v_fma_f32 v63, v2, v67, v70
	v_fma_f32 v66, v3, v62, v59
	v_fma_f32 v58, v2, v62, v58
	v_fma_f32 v58, -v3, v63, v58
	v_fma_f32 v59, v2, v63, v66
	v_fma_f32 v62, v3, v58, v55
	v_fma_f32 v54, v2, v58, v54
	v_fma_f32 v54, -v3, v59, v54
	v_fma_f32 v55, v2, v59, v62
	v_fma_f32 v58, v3, v54, v51
	v_fma_f32 v50, v2, v54, v50
	v_fma_f32 v50, -v3, v55, v50
	v_fma_f32 v51, v2, v55, v58
	v_mul_f32_e32 v54, v3, v50
	v_fmac_f32_e32 v54, v2, v51
	v_mul_f32_e32 v51, v3, v51
	s_waitcnt lgkmcnt(14)
	v_add_f32_e32 v54, v54, v107
	v_fma_f32 v50, v2, v50, -v51
	v_mul_f32_e32 v55, v2, v54
	v_add_f32_e32 v50, v50, v106
	v_mul_f32_e32 v54, v3, v54
	v_fmac_f32_e32 v55, v3, v50
	v_fma_f32 v50, v2, v50, -v54
	v_add_f32_e32 v50, v100, v50
	v_add_f32_e32 v51, v101, v55
	s_waitcnt lgkmcnt(13)
	v_fma_f32 v54, v3, v50, v93
	v_fma_f32 v50, v2, v50, v92
	v_fma_f32 v50, -v3, v51, v50
	v_fma_f32 v54, v2, v51, v54
	s_waitcnt lgkmcnt(12)
	v_fma_f32 v51, v3, v50, v87
	v_fma_f32 v50, v2, v50, v86
	v_fma_f32 v50, -v3, v54, v50
	v_fma_f32 v51, v2, v54, v51
	s_waitcnt lgkmcnt(11)
	v_fma_f32 v54, v3, v50, v81
	v_fma_f32 v50, v2, v50, v80
	v_fma_f32 v50, -v3, v51, v50
	v_fma_f32 v54, v2, v51, v54
	s_waitcnt lgkmcnt(10)
	v_fma_f32 v51, v3, v50, v75
	v_fma_f32 v50, v2, v50, v74
	v_fma_f32 v50, -v3, v54, v50
	v_fma_f32 v51, v2, v54, v51
	s_waitcnt lgkmcnt(9)
	v_fma_f32 v54, v3, v50, v69
	v_fma_f32 v50, v2, v50, v68
	v_fma_f32 v50, -v3, v51, v50
	v_fma_f32 v54, v2, v51, v54
	s_waitcnt lgkmcnt(8)
	v_fma_f32 v51, v3, v50, v65
	v_fma_f32 v50, v2, v50, v64
	v_fma_f32 v50, -v3, v54, v50
	v_fma_f32 v51, v2, v54, v51
	s_waitcnt lgkmcnt(7)
	v_fma_f32 v54, v3, v50, v61
	v_fma_f32 v50, v2, v50, v60
	v_fma_f32 v50, -v3, v51, v50
	v_fma_f32 v54, v2, v51, v54
	s_waitcnt lgkmcnt(6)
	v_fma_f32 v51, v3, v50, v57
	v_fma_f32 v50, v2, v50, v56
	v_fma_f32 v50, -v3, v54, v50
	v_fma_f32 v51, v2, v54, v51
	s_waitcnt lgkmcnt(5)
	v_fma_f32 v54, v3, v50, v53
	v_fma_f32 v50, v2, v50, v52
	v_fma_f32 v50, -v3, v51, v50
	v_fma_f32 v53, v2, v51, v54
	s_waitcnt lgkmcnt(4)
	v_fma_f32 v51, v3, v50, v49
	v_fma_f32 v48, v2, v50, v48
	v_fma_f32 v48, -v3, v53, v48
	v_fma_f32 v49, v2, v53, v51
	s_waitcnt lgkmcnt(3)
	v_fma_f32 v50, v3, v48, v47
	v_fma_f32 v46, v2, v48, v46
	v_fma_f32 v46, -v3, v49, v46
	v_fma_f32 v47, v2, v49, v50
	s_waitcnt lgkmcnt(2)
	v_fma_f32 v48, v3, v46, v45
	v_fma_f32 v44, v2, v46, v44
	v_fma_f32 v44, -v3, v47, v44
	v_fma_f32 v45, v2, v47, v48
	s_waitcnt lgkmcnt(0)
	v_mfma_f32_16x16x32_bf16 v[32:35], v[36:39], v[32:35], 0
	v_fma_f32 v46, v3, v44, v43
	v_fma_f32 v42, v2, v44, v42
	v_fma_f32 v42, -v3, v45, v42
	v_fma_f32 v43, v2, v45, v46
	v_mfma_f32_16x16x32_bf16 v[28:31], v[36:39], v[28:31], 0
	v_mfma_f32_16x16x32_bf16 v[20:23], v[36:39], v[20:23], 0
	s_nop 1
	ds_write2_b32 v0, v32, v28 offset1:16
	ds_write2_b32 v0, v33, v29 offset0:132 offset1:148
	ds_write2_b32 v137, v34, v30 offset0:8 offset1:24
	v_mfma_f32_16x16x32_bf16 v[12:15], v[36:39], v[12:15], 0
	ds_write2_b32 v137, v35, v31 offset0:140 offset1:156
	s_nop 6
	ds_write2_b32 v0, v20, v12 offset0:32 offset1:48
	ds_write2_b32 v0, v21, v13 offset0:164 offset1:180
	v_mfma_f32_16x16x32_bf16 v[24:27], v[36:39], v[24:27], 0
	v_fma_f32 v44, v3, v42, v41
	v_fma_f32 v40, v2, v42, v40
	v_fma_f32 v40, -v3, v43, v40
	v_fma_f32 v41, v2, v43, v44
	s_lshl_b32 s11, s10, 1
	s_mul_i32 s1, s10, 0x88
	v_mfma_f32_16x16x32_bf16 v[16:19], v[36:39], v[16:19], 0
	ds_write2_b32 v137, v22, v14 offset0:40 offset1:56
	ds_write2_b32 v137, v23, v15 offset0:172 offset1:188
	s_nop 5
	ds_write2_b32 v0, v24, v16 offset0:64 offset1:80
	ds_write2_b32 v0, v25, v17 offset0:196 offset1:212
	ds_write2_b32 v137, v26, v18 offset0:72 offset1:88
	ds_write2_b32 v137, v27, v19 offset0:204 offset1:220
	v_mfma_f32_16x16x32_bf16 v[8:11], v[36:39], v[8:11], 0
	s_ashr_i32 s10, s9, 31
	s_mul_hi_i32 s5, s11, 0x44
	s_add_u32 s4, s1, s9
	v_mfma_f32_16x16x32_bf16 v[4:7], v[36:39], v[4:7], 0
	s_nop 7
	ds_write2_b32 v0, v8, v4 offset0:96 offset1:112
	ds_write2_b32 v0, v9, v5 offset0:228 offset1:244
	ds_write2_b32 v137, v10, v6 offset0:104 offset1:120
	ds_write2_b32 v137, v11, v7 offset0:236 offset1:252
	s_waitcnt lgkmcnt(0)
	v_mul_f32_e32 v0, v3, v41
	ds_read2st64_b32 v[4:5], v138 offset0:12 offset1:13
	ds_read2st64_b32 v[6:7], v139 offset0:14 offset1:15
	ds_read2st64_b32 v[8:9], v140 offset0:16 offset1:17
	ds_read2st64_b32 v[10:11], v141 offset0:18 offset1:19
	ds_read2st64_b32 v[12:13], v146 offset0:20 offset1:21
	ds_read2st64_b32 v[14:15], v147 offset0:22 offset1:23
	ds_read2st64_b32 v[16:17], v148 offset0:24 offset1:25
	ds_read2st64_b32 v[18:19], v149 offset0:26 offset1:27
	ds_read2st64_b32 v[20:21], v150 offset0:28 offset1:29
	ds_read2st64_b32 v[22:23], v151 offset0:30 offset1:31
	ds_read2st64_b32 v[24:25], v152 offset0:32 offset1:33
	ds_read2st64_b32 v[26:27], v153 offset0:34 offset1:35
	ds_read2st64_b32 v[28:29], v154 offset0:36 offset1:37
	ds_read2st64_b32 v[30:31], v155 offset0:38 offset1:39
	ds_read2st64_b32 v[32:33], v156 offset0:40 offset1:41
	ds_read2st64_b32 v[34:35], v157 offset0:42 offset1:43
	v_fma_f32 v0, v2, v40, -v0
	s_waitcnt lgkmcnt(14)
	v_add_f32_e32 v0, v0, v4
	v_mul_f32_e32 v4, v3, v40
	v_fmac_f32_e32 v4, v2, v41
	v_add_f32_e32 v4, v4, v5
	v_mul_f32_e32 v5, v3, v4
	v_mul_f32_e32 v4, v2, v4
	v_fmac_f32_e32 v4, v3, v0
	v_fma_f32 v5, v2, v0, -v5
	v_add_f32_e32 v0, v7, v4
	v_add_f32_e32 v5, v6, v5
	s_waitcnt lgkmcnt(13)
	v_fma_f32 v4, -v0, v3, v8
	v_fma_f32 v0, v0, v2, v9
	v_fma_f32 v0, v5, v3, v0
	v_fma_f32 v4, v5, v2, v4
	s_waitcnt lgkmcnt(12)
	v_fma_f32 v5, -v0, v3, v10
	v_fma_f32 v0, v0, v2, v11
	v_fma_f32 v0, v4, v3, v0
	v_fma_f32 v5, v4, v2, v5
	s_waitcnt lgkmcnt(11)
	v_fma_f32 v4, -v0, v3, v12
	v_fma_f32 v0, v0, v2, v13
	v_fma_f32 v0, v5, v3, v0
	v_fma_f32 v4, v5, v2, v4
	s_waitcnt lgkmcnt(10)
	v_fma_f32 v5, -v0, v3, v14
	v_fma_f32 v0, v0, v2, v15
	v_fma_f32 v0, v4, v3, v0
	v_fma_f32 v5, v4, v2, v5
	s_waitcnt lgkmcnt(9)
	v_fma_f32 v4, -v0, v3, v16
	v_fma_f32 v0, v0, v2, v17
	v_fma_f32 v0, v5, v3, v0
	v_fma_f32 v4, v5, v2, v4
	s_waitcnt lgkmcnt(8)
	v_fma_f32 v5, -v0, v3, v18
	v_fma_f32 v0, v0, v2, v19
	v_fma_f32 v0, v4, v3, v0
	v_fma_f32 v5, v4, v2, v5
	s_waitcnt lgkmcnt(7)
	v_fma_f32 v4, -v0, v3, v20
	v_fma_f32 v0, v0, v2, v21
	v_fma_f32 v0, v5, v3, v0
	v_fma_f32 v4, v5, v2, v4
	s_waitcnt lgkmcnt(6)
	v_fma_f32 v5, -v0, v3, v22
	v_fma_f32 v0, v0, v2, v23
	v_fma_f32 v0, v4, v3, v0
	v_fma_f32 v5, v4, v2, v5
	s_waitcnt lgkmcnt(5)
	v_fma_f32 v4, -v0, v3, v24
	v_fma_f32 v0, v0, v2, v25
	v_fma_f32 v0, v5, v3, v0
	v_fma_f32 v4, v5, v2, v4
	s_waitcnt lgkmcnt(4)
	v_fma_f32 v5, -v0, v3, v26
	v_fma_f32 v0, v0, v2, v27
	v_fma_f32 v0, v4, v3, v0
	v_fma_f32 v5, v4, v2, v5
	s_waitcnt lgkmcnt(3)
	v_fma_f32 v4, -v0, v3, v28
	v_fma_f32 v0, v0, v2, v29
	v_fma_f32 v0, v5, v3, v0
	v_fma_f32 v4, v5, v2, v4
	s_waitcnt lgkmcnt(2)
	v_fma_f32 v5, -v0, v3, v30
	v_fma_f32 v0, v0, v2, v31
	v_fma_f32 v0, v4, v3, v0
	v_fma_f32 v5, v4, v2, v5
	s_waitcnt lgkmcnt(1)
	v_fma_f32 v4, v3, v5, v33
	v_fma_f32 v6, v2, v5, v32
	v_fma_f32 v6, -v3, v0, v6
	v_fma_f32 v0, v2, v0, v4
	v_mul_f32_e32 v4, v3, v0
	v_mul_f32_e32 v3, v3, v6
	v_fmac_f32_e32 v3, v2, v0
	s_waitcnt lgkmcnt(0)
	v_mov_b32_e32 v0, s59
	v_fma_f32 v4, v2, v6, -v4
	s_waitcnt lgkmcnt(0)
	v_add_f32_e32 v5, v35, v3
	ds_read_b64 v[2:3], v0
	s_addc_u32 s5, s5, s10
	s_ashr_i32 s1, s0, 31
	s_lshl_b64 s[22:23], s[4:5], 10
	s_lshl_b64 s[4:5], s[0:1], 6
	s_add_u32 s1, s22, s4
	s_addc_u32 s17, s23, s5
	v_or_b32_e32 v6, s1, v136
	v_mov_b32_e32 v7, s17
	s_waitcnt lgkmcnt(0)
	v_readfirstlane_b32 s1, v3
	v_readfirstlane_b32 s17, v2
	v_add_f32_e32 v4, v34, v4
	v_mov_b32_e32 v3, s1
	v_mov_b32_e32 v2, s17
	v_lshl_add_u64 v[2:3], v[6:7], 3, v[2:3]
	s_mov_b32 s1, 0xc00000
	v_add_co_u32_e32 v2, vcc, s1, v2
	v_mov_b32_e32 v42, v204
	s_nop 0
	v_addc_co_u32_e32 v3, vcc, 0, v3, vcc
	global_store_dwordx2 v[2:3], v[4:5], off
	ds_read_b64 v[2:3], v0
	v_readfirstlane_b32 s1, v42
	s_lshr_b32 s1, s1, 6
	s_mulk_i32 s1, 0x3e00
	s_add_i32 s17, s1, 0
	v_readlane_b32 s1, v244, 25
	v_and_b32_e32 v136, 63, v42
	s_add_i32 s0, s0, s1
	s_waitcnt lgkmcnt(0)
	v_readfirstlane_b32 s22, v2
	v_lshl_or_b32 v2, s0, 6, v136
	v_readfirstlane_b32 s23, v3
	v_ashrrev_i32_e32 v3, 31, v2
	s_mov_b32 s1, 0x200000
	v_lshl_add_u64 v[2:3], v[2:3], 4, s[22:23]
	v_add_co_u32_e32 v2, vcc, s1, v2
	s_ashr_i32 s1, s0, 31
	s_lshl_b64 s[0:1], s[0:1], 13
	s_add_u32 s0, s22, s0
	v_and_b32_e32 v37, 15, v42
	s_addc_u32 s1, s23, s1
	v_and_b32_e32 v0, 48, v42
	v_lshl_add_u64 v[4:5], s[0:1], 0, v[0:1]
	v_lshlrev_b32_e32 v6, 6, v37
	v_mov_b32_e32 v7, v1
	v_lshl_add_u64 v[6:7], v[4:5], 0, v[6:7]
	s_mov_b64 s[0:1], 0x240000
	v_addc_co_u32_e32 v3, vcc, 0, v3, vcc
	v_lshl_add_u64 v[8:9], v[6:7], 0, s[0:1]
	s_mov_b32 s0, 0x240000
	v_add_co_u32_e32 v10, vcc, s0, v6
	global_load_dwordx4 v[2:5], v[2:3], off
	s_nop 0
	global_load_dwordx4 v[28:31], v[8:9], off offset:1024
	global_load_dwordx4 v[24:27], v[8:9], off offset:2048
	global_load_dwordx4 v[16:19], v[8:9], off offset:3072
	v_addc_co_u32_e32 v11, vcc, 0, v7, vcc
	s_waitcnt vmcnt(0) lgkmcnt(0)
	v_add_co_u32_e32 v4, vcc, 0x241000, v6
	v_mul_u32_u24_e32 v38, 48, v37
	s_nop 0
	v_addc_co_u32_e32 v5, vcc, 0, v7, vcc
	global_load_dwordx4 v[32:35], v[10:11], off
	global_load_dwordx4 v[20:23], v[4:5], off
	global_load_dwordx4 v[12:15], v[4:5], off offset:1024
	s_nop 0
	global_load_dwordx4 v[8:11], v[4:5], off offset:2048
	s_nop 0
	global_load_dwordx4 v[4:7], v[4:5], off offset:3072
	v_cmp_gt_u32_e32 vcc, 32, v136
	v_mov_b32_e32 v36, 0
	v_add3_u32 v159, s17, v38, v0
	v_mov_b32_e32 v38, 0
	v_mov_b32_e32 v39, 0
	v_mov_b32_e32 v40, 0
	v_mov_b32_e32 v41, 0
	s_and_saveexec_b64 s[0:1], vcc
	ds_read_b128 v[38:41], v159 offset:2304
	s_or_b64 exec, exec, s[0:1]
	s_waitcnt vmcnt(0) lgkmcnt(0)
	v_mfma_f32_16x16x32_bf16 v[44:47], v[38:41], v[32:35], 0
	v_bfe_u32 v43, v42, 4, 2
	v_lshlrev_b32_e32 v37, 2, v37
	v_mul_u32_u24_e32 v43, 0x840, v43
	v_mfma_f32_16x16x32_bf16 v[48:51], v[38:41], v[28:31], 0
	v_add3_u32 v37, s17, v37, v43
	v_add_u32_e32 v137, 0xc00, v37
	v_add_u32_e32 v138, 0x1000, v37
	v_mfma_f32_16x16x32_bf16 v[52:55], v[38:41], v[24:27], 0
	v_lshl_add_u32 v139, v136, 2, s17
	s_nop 2
	ds_write2_b32 v137, v44, v48 offset1:16
	ds_write2_b32 v137, v45, v49 offset0:132 offset1:148
	v_mfma_f32_16x16x32_bf16 v[56:59], v[38:41], v[16:19], 0
	ds_write2_b32 v138, v46, v50 offset0:8 offset1:24
	ds_write2_b32 v138, v47, v51 offset0:140 offset1:156
	s_nop 5
	ds_write2_b32 v137, v52, v56 offset0:32 offset1:48
	ds_write2_b32 v137, v53, v57 offset0:164 offset1:180
	v_mfma_f32_16x16x32_bf16 v[60:63], v[38:41], v[20:23], 0
	v_add_u32_e32 v140, 0xf0, v139
	v_add_u32_e32 v141, 0xe0, v139
	v_add_u32_e32 v146, 0xd0, v139
	v_mfma_f32_16x16x32_bf16 v[44:47], v[38:41], v[12:15], 0
	ds_write2_b32 v138, v54, v58 offset0:40 offset1:56
	ds_write2_b32 v138, v55, v59 offset0:172 offset1:188
	s_nop 5
	ds_write2_b32 v137, v60, v44 offset0:64 offset1:80
	ds_write2_b32 v137, v61, v45 offset0:196 offset1:212
	ds_write2_b32 v138, v62, v46 offset0:72 offset1:88
	ds_write2_b32 v138, v63, v47 offset0:204 offset1:220
	v_mfma_f32_16x16x32_bf16 v[48:51], v[38:41], v[8:11], 0
	v_add_u32_e32 v147, 0xc0, v139
	v_add_u32_e32 v148, 0xb0, v139
	v_add_u32_e32 v149, 0xa0, v139
	v_mfma_f32_16x16x32_bf16 v[38:41], v[38:41], v[4:7], 0
	s_nop 7
	ds_write2_b32 v137, v48, v38 offset0:96 offset1:112
	ds_write2_b32 v137, v49, v39 offset0:228 offset1:244
	ds_write2_b32 v138, v50, v40 offset0:104 offset1:120
	ds_write2_b32 v138, v51, v41 offset0:236 offset1:252
	s_waitcnt lgkmcnt(0)
	v_add_u32_e32 v150, 0x90, v139
	v_add_u32_e32 v151, 0x80, v139
	v_add_u32_e32 v152, 0x70, v139
	v_add_u32_e32 v153, 0x60, v139
	v_add_u32_e32 v154, 0x50, v139
	v_add_u32_e32 v155, 64, v139
	v_add_u32_e32 v156, 48, v139
	v_add_u32_e32 v157, 32, v139
	v_add_u32_e32 v158, 16, v139
	ds_read2st64_b32 v[134:135], v140 offset0:42 offset1:43
	ds_read2st64_b32 v[132:133], v141 offset0:40 offset1:41
	ds_read2st64_b32 v[130:131], v146 offset0:38 offset1:39
	ds_read2st64_b32 v[126:127], v147 offset0:36 offset1:37
	ds_read2st64_b32 v[122:123], v148 offset0:34 offset1:35
	ds_read2st64_b32 v[118:119], v149 offset0:32 offset1:33
	ds_read2st64_b32 v[116:117], v150 offset0:30 offset1:31
	ds_read2st64_b32 v[112:113], v151 offset0:28 offset1:29
	ds_read2st64_b32 v[108:109], v152 offset0:26 offset1:27
	ds_read2st64_b32 v[102:103], v153 offset0:24 offset1:25
	ds_read2st64_b32 v[96:97], v154 offset0:22 offset1:23
	ds_read2st64_b32 v[90:91], v155 offset0:20 offset1:21
	ds_read2st64_b32 v[86:87], v156 offset0:18 offset1:19
	ds_read2st64_b32 v[82:83], v157 offset0:16 offset1:17
	ds_read2st64_b32 v[76:77], v158 offset0:14 offset1:15
	ds_read2st64_b32 v[70:71], v139 offset0:12 offset1:13
	s_waitcnt lgkmcnt(0)
	v_mov_b32_e32 v37, 0
	v_mov_b32_e32 v38, 0
	v_mov_b32_e32 v39, 0
	s_and_saveexec_b64 s[0:1], vcc
	v_or_b32_e32 v36, 0xfffff0, v42
	v_mul_i32_i24_e32 v36, 48, v36
	v_add3_u32 v0, s17, v36, v0
	ds_read_b128 v[36:39], v0 offset:2304
	s_or_b64 exec, exec, s[0:1]
	s_waitcnt lgkmcnt(0)
	v_mfma_f32_16x16x32_bf16 v[40:43], v[36:39], v[32:35], 0
	v_mfma_f32_16x16x32_bf16 v[44:47], v[36:39], v[28:31], 0
	s_nop 7
	ds_write2_b32 v137, v40, v44 offset1:16
	ds_write2_b32 v137, v41, v45 offset0:132 offset1:148
	ds_write2_b32 v138, v42, v46 offset0:8 offset1:24
	v_mfma_f32_16x16x32_bf16 v[48:51], v[36:39], v[24:27], 0
	v_mfma_f32_16x16x32_bf16 v[52:55], v[36:39], v[16:19], 0
	ds_write2_b32 v138, v43, v47 offset0:140 offset1:156
	s_nop 6
	ds_write2_b32 v137, v48, v52 offset0:32 offset1:48
	ds_write2_b32 v137, v49, v53 offset0:164 offset1:180
	v_mfma_f32_16x16x32_bf16 v[56:59], v[36:39], v[20:23], 0
	v_mfma_f32_16x16x32_bf16 v[40:43], v[36:39], v[12:15], 0
	ds_write2_b32 v138, v50, v54 offset0:40 offset1:56
	ds_write2_b32 v138, v51, v55 offset0:172 offset1:188
	s_nop 5
	ds_write2_b32 v137, v56, v40 offset0:64 offset1:80
	ds_write2_b32 v137, v57, v41 offset0:196 offset1:212
	ds_write2_b32 v138, v58, v42 offset0:72 offset1:88
	ds_write2_b32 v138, v59, v43 offset0:204 offset1:220
	v_mfma_f32_16x16x32_bf16 v[44:47], v[36:39], v[8:11], 0
	v_mov_b32_e32 v40, 0
	v_mov_b32_e32 v41, 0
	v_mfma_f32_16x16x32_bf16 v[36:39], v[36:39], v[4:7], 0
	s_nop 7
	ds_write2_b32 v137, v44, v36 offset0:96 offset1:112
	ds_write2_b32 v137, v45, v37 offset0:228 offset1:244
	ds_write2_b32 v138, v46, v38 offset0:104 offset1:120
	ds_write2_b32 v138, v47, v39 offset0:236 offset1:252
	s_waitcnt lgkmcnt(0)
	ds_read2st64_b32 v[128:129], v140 offset0:42 offset1:43
	ds_read2st64_b32 v[124:125], v141 offset0:40 offset1:41
	ds_read2st64_b32 v[120:121], v146 offset0:38 offset1:39
	ds_read2st64_b32 v[114:115], v147 offset0:36 offset1:37
	ds_read2st64_b32 v[110:111], v148 offset0:34 offset1:35
	ds_read2st64_b32 v[104:105], v149 offset0:32 offset1:33
	ds_read2st64_b32 v[98:99], v150 offset0:30 offset1:31
	ds_read2st64_b32 v[92:93], v151 offset0:28 offset1:29
	ds_read2st64_b32 v[84:85], v152 offset0:26 offset1:27
	ds_read2st64_b32 v[78:79], v153 offset0:24 offset1:25
	ds_read2st64_b32 v[72:73], v154 offset0:22 offset1:23
	ds_read2st64_b32 v[66:67], v155 offset0:20 offset1:21
	ds_read2st64_b32 v[62:63], v156 offset0:18 offset1:19
	ds_read2st64_b32 v[58:59], v157 offset0:16 offset1:17
	ds_read2st64_b32 v[54:55], v158 offset0:14 offset1:15
	ds_read2st64_b32 v[50:51], v139 offset0:12 offset1:13
	s_waitcnt lgkmcnt(0)
	v_mov_b32_e32 v36, 0
	v_mov_b32_e32 v38, 0
	v_mov_b32_e32 v39, 0
	s_and_saveexec_b64 s[0:1], vcc
	ds_read_b128 v[38:41], v159 offset:768
	s_or_b64 exec, exec, s[0:1]
	s_waitcnt lgkmcnt(0)
	v_mfma_f32_16x16x32_bf16 v[42:45], v[38:41], v[32:35], 0
	v_mov_b32_e32 v37, 0
	v_mfma_f32_16x16x32_bf16 v[46:49], v[38:41], v[28:31], 0
	s_nop 7
	ds_write2_b32 v137, v42, v46 offset1:16
	ds_write2_b32 v137, v43, v47 offset0:132 offset1:148
	ds_write2_b32 v138, v44, v48 offset0:8 offset1:24
	v_mfma_f32_16x16x32_bf16 v[160:163], v[38:41], v[24:27], 0
	v_mfma_f32_16x16x32_bf16 v[164:167], v[38:41], v[16:19], 0
	ds_write2_b32 v138, v45, v49 offset0:140 offset1:156
	s_nop 6
	ds_write2_b32 v137, v160, v164 offset0:32 offset1:48
	ds_write2_b32 v137, v161, v165 offset0:164 offset1:180
	v_mfma_f32_16x16x32_bf16 v[168:171], v[38:41], v[20:23], 0
	v_mfma_f32_16x16x32_bf16 v[42:45], v[38:41], v[12:15], 0
	ds_write2_b32 v138, v162, v166 offset0:40 offset1:56
	ds_write2_b32 v138, v163, v167 offset0:172 offset1:188
	s_nop 5
	ds_write2_b32 v137, v168, v42 offset0:64 offset1:80
	ds_write2_b32 v137, v169, v43 offset0:196 offset1:212
	ds_write2_b32 v138, v170, v44 offset0:72 offset1:88
	ds_write2_b32 v138, v171, v45 offset0:204 offset1:220
	v_mfma_f32_16x16x32_bf16 v[46:49], v[38:41], v[8:11], 0
	v_mfma_f32_16x16x32_bf16 v[38:41], v[38:41], v[4:7], 0
	s_nop 7
	ds_write2_b32 v137, v46, v38 offset0:96 offset1:112
	ds_write2_b32 v137, v47, v39 offset0:228 offset1:244
	ds_write2_b32 v138, v48, v40 offset0:104 offset1:120
	ds_write2_b32 v138, v49, v41 offset0:236 offset1:252
	s_waitcnt lgkmcnt(0)
	ds_read2st64_b32 v[106:107], v140 offset0:42 offset1:43
	ds_read2st64_b32 v[100:101], v141 offset0:40 offset1:41
	ds_read2st64_b32 v[94:95], v146 offset0:38 offset1:39
	ds_read2st64_b32 v[88:89], v147 offset0:36 offset1:37
	ds_read2st64_b32 v[80:81], v148 offset0:34 offset1:35
	ds_read2st64_b32 v[74:75], v149 offset0:32 offset1:33
	ds_read2st64_b32 v[68:69], v150 offset0:30 offset1:31
	ds_read2st64_b32 v[64:65], v151 offset0:28 offset1:29
	ds_read2st64_b32 v[60:61], v152 offset0:26 offset1:27
	ds_read2st64_b32 v[56:57], v153 offset0:24 offset1:25
	ds_read2st64_b32 v[52:53], v154 offset0:22 offset1:23
	ds_read2st64_b32 v[48:49], v155 offset0:20 offset1:21
	ds_read2st64_b32 v[46:47], v156 offset0:18 offset1:19
	ds_read2st64_b32 v[44:45], v157 offset0:16 offset1:17
	ds_read2st64_b32 v[42:43], v158 offset0:14 offset1:15
	ds_read2st64_b32 v[40:41], v139 offset0:12 offset1:13
	s_waitcnt lgkmcnt(0)
	v_mov_b32_e32 v38, 0
	v_mov_b32_e32 v39, 0
	s_and_saveexec_b64 s[0:1], vcc
	s_cbranch_execz .LBB0_594
	ds_read_b128 v[36:39], v159
	s_branch .LBB0_594
